# hand-written P4 attention (3-stage K/V prefetch, straight-line softmax) + hand-written conv with batched loads
# speedup vs baseline: 1.0062x; 1.0062x over previous
.LBB0_429:
	s_and_b32 s79, s4, s6
	s_and_b32 s78, s6, 3
	v_sub_u32_e64 v0, s79, 4 clamp
	s_lshl_b32 s4, s78, 1
	v_readfirstlane_b32 s52, v0
	v_sub_u32_e64 v0, s79, 3 clamp
	s_min_u32 s85, s52, s48
	v_min_u32_e32 v0, s48, v0
	s_or_b32 s4, s4, s66
	s_lshl_b32 s22, s4, 8
	v_cmp_eq_u32_e32 vcc, s85, v0
	s_lshl_b32 s87, s4, 6
	v_lshl_add_u64 v[192:193], v[180:181], 0, s[22:23]
	s_mov_b64 s[4:5], -1
	s_and_b64 vcc, exec, vcc
	s_mul_i32 s50, s77, 0x60
	s_mul_i32 s81, s78, 0xe88
	s_mul_i32 s82, s85, 0x7c
	s_mul_i32 s80, s79, 0x7c
	s_cmp_lg_u64 vcc, 0
	s_cselect_b32 s94, 0, 1
	s_mul_i32 s93, s94, 3
	s_add_u32 s93, s93, 8
	s_ashr_i32 s47, s46, 31
	s_lshl_b32 s83, s78, 1
	s_or_b32 s83, s83, s66
	s_lshr_b32 s96, s67, 1
	s_add_u32 s96, s96, s67
	s_lshl_b32 s96, s96, 3
	v_mbcnt_lo_u32_b32 v162, -1, 0
	v_mbcnt_hi_u32_b32 v162, -1, v162
	v_and_b32_e32 v163, 15, v162
	v_lshrrev_b32_e32 v164, 4, v162
	v_lshl_add_u32 v165, s67, 4, v163
	v_lshlrev_b32_e32 v0, 10, v165
	v_lshl_add_u32 v0, v164, 4, v0
	v_lshrrev_b32_e32 v166, 2, v163
	v_lshlrev_b32_e32 v166, 3, v166
	v_and_b32_e32 v214, 3, v163
	v_add_u32_e32 v214, v214, v166
	v_lshlrev_b32_e32 v214, 10, v214
	v_lshl_add_u32 v214, v164, 4, v214
	s_lshl_b32 s97, s77, 1
	v_mul_lo_u32 v246, v163, s97
	v_lshl_add_u32 v246, v164, 4, v246
	v_add_u32_e32 v166, -8, v165
	v_med3_i32 v166, v166, 0, 48
	v_lshl_add_u32 v167, v164, 3, s96
	v_sub_u32_e32 v168, v167, v166
	v_cmp_gt_u32_e64 s[4:5], 16, v168
	v_add_u32_e32 v169, 1, v168
	v_cmp_gt_u32_e64 s[6:7], 16, v169
	v_add_u32_e32 v169, 2, v168
	v_cmp_gt_u32_e64 s[8:9], 16, v169
	v_add_u32_e32 v169, 3, v168
	v_cmp_gt_u32_e64 s[10:11], 16, v169
	v_add_u32_e32 v169, 4, v168
	v_cmp_gt_u32_e64 s[12:13], 16, v169
	v_add_u32_e32 v169, 5, v168
	v_cmp_gt_u32_e64 s[14:15], 16, v169
	v_add_u32_e32 v169, 6, v168
	v_cmp_gt_u32_e64 s[16:17], 16, v169
	v_add_u32_e32 v169, 7, v168
	v_cmp_gt_u32_e64 s[18:19], 16, v169
	s_mul_i32 s97, s83, 0x744
	s_sub_i32 s51, s85, s79
	s_add_i32 s51, s51, 4
	s_mul_i32 s51, s51, 0x7c
	s_add_i32 s97, s97, s51
	s_add_i32 s97, s97, 0x13c
	v_sub_u32_e32 v169, v167, v165
	v_lshl_add_u32 v215, v169, 2, s97
	s_lshl_b32 s51, s79, 6
	s_add_u32 s51, s51, s46
	s_lshl_b32 s54, s83, 7
	s_lshl_b32 s80, s51, 10
	s_add_u32 s80, s80, s54
	s_add_u32 s98, s30, 0xe000000
	s_addc_u32 s99, s31, 0
	s_add_u32 s98, s98, s80
	s_addc_u32 s99, s99, 0
	global_load_dwordx4 v[66:69], v0, s[98:99]
	global_load_dwordx4 v[70:73], v0, s[98:99] offset:64
	s_add_u32 s98, s98, 0x10000
	s_addc_u32 s99, s99, 0
	global_load_dwordx4 v[74:77], v0, s[98:99]
	global_load_dwordx4 v[78:81], v0, s[98:99] offset:64
	s_add_u32 s98, s98, 0x10000
	s_addc_u32 s99, s99, 0
	global_load_dwordx4 v[82:85], v0, s[98:99]
	global_load_dwordx4 v[86:89], v0, s[98:99] offset:64
	s_add_u32 s98, s98, 0x10000
	s_addc_u32 s99, s99, 0
	global_load_dwordx4 v[90:93], v0, s[98:99]
	global_load_dwordx4 v[94:97], v0, s[98:99] offset:64
	s_lshl_b32 s80, s85, 6
	s_add_u32 s80, s80, s46
	s_add_u32 s80, s80, s96
	s_lshl_b32 s80, s80, 10
	s_add_u32 s80, s80, s54
	s_add_u32 s80, s80, 0x800
	s_add_u32 s88, s30, 0x13000000
	s_addc_u32 s89, s31, 0
	s_add_u32 s88, s88, s80
	s_addc_u32 s89, s89, 0
	s_lshl_b32 s80, s83, 6
	s_mul_i32 s80, s80, s77
	s_lshl_b32 s55, s85, 6
	s_add_u32 s80, s80, s55
	s_add_u32 s80, s80, s96
	s_lshl_b32 s80, s80, 1
	s_lshl_b32 s55, s46, 10
	s_add_u32 s80, s80, s55
	s_add_u32 s90, s30, 0x18000000
	s_addc_u32 s91, s31, 0
	s_add_u32 s90, s90, s80
	s_addc_u32 s91, s91, 0
	s_lshl_b32 s80, s77, 5
	s_add_u32 s98, s90, s80
	s_addc_u32 s99, s91, 0
	s_add_u32 s100, s98, s80
	s_addc_u32 s101, s99, 0
	s_add_u32 s52, s100, s80
	s_addc_u32 s53, s101, 0
	global_load_dwordx4 v[98:101], v214, s[88:89] offset:-2048
	global_load_dwordx4 v[102:105], v214, s[88:89] offset:-1984
	global_load_dwordx4 v[106:109], v214, s[88:89] offset:2048
	global_load_dwordx4 v[110:113], v214, s[88:89] offset:2112
	global_load_dwordx4 v[114:117], v246, s[90:91]
	global_load_dwordx4 v[118:121], v246, s[98:99]
	global_load_dwordx4 v[122:125], v246, s[100:101]
	global_load_dwordx4 v[126:129], v246, s[52:53]
	s_add_u32 s88, s88, 0x10000
	s_addc_u32 s89, s89, 0
	s_add_u32 s90, s90, 0x80
	s_addc_u32 s91, s91, 0
	s_add_u32 s98, s98, 0x80
	s_addc_u32 s99, s99, 0
	s_add_u32 s100, s100, 0x80
	s_addc_u32 s101, s101, 0
	s_add_u32 s52, s52, 0x80
	s_addc_u32 s53, s53, 0
	global_load_dwordx4 v[130:133], v214, s[88:89] offset:-2048
	global_load_dwordx4 v[134:137], v214, s[88:89] offset:-1984
	global_load_dwordx4 v[138:141], v214, s[88:89] offset:2048
	global_load_dwordx4 v[142:145], v214, s[88:89] offset:2112
	global_load_dwordx4 v[146:149], v246, s[90:91]
	global_load_dwordx4 v[150:153], v246, s[98:99]
	global_load_dwordx4 v[154:157], v246, s[100:101]
	global_load_dwordx4 v[158:161], v246, s[52:53]
	s_add_u32 s88, s88, 0x10000
	s_addc_u32 s89, s89, 0
	s_add_u32 s90, s90, 0x80
	s_addc_u32 s91, s91, 0
	s_add_u32 s98, s98, 0x80
	s_addc_u32 s99, s99, 0
	s_add_u32 s100, s100, 0x80
	s_addc_u32 s101, s101, 0
	s_add_u32 s52, s52, 0x80
	s_addc_u32 s53, s53, 0
	v_mov_b32_e32 v2, 0
	v_mov_b32_e32 v3, 0
	v_mov_b32_e32 v4, 0
	v_mov_b32_e32 v5, 0
	v_mov_b32_e32 v6, 0
	v_mov_b32_e32 v7, 0
	v_mov_b32_e32 v8, 0
	v_mov_b32_e32 v9, 0
	v_mov_b32_e32 v10, 0
	v_mov_b32_e32 v11, 0
	v_mov_b32_e32 v12, 0
	v_mov_b32_e32 v13, 0
	v_mov_b32_e32 v14, 0
	v_mov_b32_e32 v15, 0
	v_mov_b32_e32 v16, 0
	v_mov_b32_e32 v17, 0
	v_mov_b32_e32 v18, 0
	v_mov_b32_e32 v19, 0
	v_mov_b32_e32 v20, 0
	v_mov_b32_e32 v21, 0
	v_mov_b32_e32 v22, 0
	v_mov_b32_e32 v23, 0
	v_mov_b32_e32 v24, 0
	v_mov_b32_e32 v25, 0
	v_mov_b32_e32 v26, 0
	v_mov_b32_e32 v27, 0
	v_mov_b32_e32 v28, 0
	v_mov_b32_e32 v29, 0
	v_mov_b32_e32 v30, 0
	v_mov_b32_e32 v31, 0
	v_mov_b32_e32 v32, 0
	v_mov_b32_e32 v33, 0
	v_mov_b32_e32 v34, 0
	v_mov_b32_e32 v35, 0
	v_mov_b32_e32 v36, 0
	v_mov_b32_e32 v37, 0
	v_mov_b32_e32 v38, 0
	v_mov_b32_e32 v39, 0
	v_mov_b32_e32 v40, 0
	v_mov_b32_e32 v41, 0
	v_mov_b32_e32 v42, 0
	v_mov_b32_e32 v43, 0
	v_mov_b32_e32 v44, 0
	v_mov_b32_e32 v45, 0
	v_mov_b32_e32 v46, 0
	v_mov_b32_e32 v47, 0
	v_mov_b32_e32 v48, 0
	v_mov_b32_e32 v49, 0
	v_mov_b32_e32 v50, 0
	v_mov_b32_e32 v51, 0
	v_mov_b32_e32 v52, 0
	v_mov_b32_e32 v53, 0
	v_mov_b32_e32 v54, 0
	v_mov_b32_e32 v55, 0
	v_mov_b32_e32 v56, 0
	v_mov_b32_e32 v57, 0
	v_mov_b32_e32 v58, 0
	v_mov_b32_e32 v59, 0
	v_mov_b32_e32 v60, 0
	v_mov_b32_e32 v61, 0
	v_mov_b32_e32 v62, 0
	v_mov_b32_e32 v63, 0
	v_mov_b32_e32 v64, 0
	v_mov_b32_e32 v65, 0
	v_mov_b32_e32 v225, 0
	v_mov_b32_e32 v226, 0
	v_mov_b32_e32 v227, 0
	v_mov_b32_e32 v229, 0
	s_mov_b32 s92, 0
.Lattn_loop:
	s_add_u32 s95, s92, 2
	s_cmp_lt_u32 s95, s93
	s_cbranch_scc0 .Lattn_nopf2_a
	global_load_dwordx4 v[194:197], v214, s[88:89] offset:-2048
	global_load_dwordx4 v[198:201], v214, s[88:89] offset:-1984
	global_load_dwordx4 v[202:205], v214, s[88:89] offset:2048
	global_load_dwordx4 v[206:209], v214, s[88:89] offset:2112
	global_load_dwordx4 v[210:213], v246, s[90:91]
	global_load_dwordx4 v[230:233], v246, s[98:99]
	global_load_dwordx4 v[234:237], v246, s[100:101]
	global_load_dwordx4 v[238:241], v246, s[52:53]
	s_add_u32 s88, s88, 0x10000
	s_addc_u32 s89, s89, 0
	s_add_u32 s90, s90, 0x80
	s_addc_u32 s91, s91, 0
	s_add_u32 s98, s98, 0x80
	s_addc_u32 s99, s99, 0
	s_add_u32 s100, s100, 0x80
	s_addc_u32 s101, s101, 0
	s_add_u32 s52, s52, 0x80
	s_addc_u32 s53, s53, 0
	s_waitcnt vmcnt(16)
	s_branch .Lattn_go_a
.Lattn_nopf2_a:
	s_add_u32 s95, s92, 1
	s_cmp_lt_u32 s95, s93
	s_cbranch_scc0 .Lattn_nopf1_a
	s_waitcnt vmcnt(8)
	s_branch .Lattn_go_a

.Lattn_go_a:
	s_cmp_lt_u32 s92, 8
	s_cbranch_scc0 .Lattn_skip_a_0
	ds_read2_b32 v[242:243], v215 offset0:93 offset1:94
	ds_read2_b32 v[244:245], v215 offset0:95 offset1:96
	ds_read2_b32 v[248:249], v215 offset0:97 offset1:98
	ds_read2_b32 v[250:251], v215 offset0:99 offset1:100
	v_mfma_f32_16x16x32_bf16 v[162:165], v[98:101], v[66:69], 0
	v_mfma_f32_16x16x32_bf16 v[162:165], v[102:105], v[70:73], v[162:165]
	v_mfma_f32_16x16x32_bf16 v[166:169], v[106:109], v[66:69], 0
	v_mfma_f32_16x16x32_bf16 v[166:169], v[110:113], v[70:73], v[166:169]
	s_waitcnt lgkmcnt(0)
	s_nop 7
	v_add_f32_e32 v242, v162, v242
	v_add_f32_e32 v243, v163, v243
	v_add_f32_e32 v244, v164, v244
	v_add_f32_e32 v245, v165, v245
	v_add_f32_e32 v248, v166, v248
	v_add_f32_e32 v249, v167, v249
	v_add_f32_e32 v250, v168, v250
	v_add_f32_e32 v251, v169, v251
	v_exp_f32_e32 v242, v242
	v_exp_f32_e32 v243, v243
	v_exp_f32_e32 v244, v244
	v_exp_f32_e32 v245, v245
	v_exp_f32_e32 v248, v248
	v_exp_f32_e32 v249, v249
	v_exp_f32_e32 v250, v250
	v_exp_f32_e32 v251, v251
	v_cndmask_b32_e64 v242, 0, v242, s[4:5]
	v_cndmask_b32_e64 v243, 0, v243, s[6:7]
	v_cndmask_b32_e64 v244, 0, v244, s[8:9]
	v_cndmask_b32_e64 v245, 0, v245, s[10:11]
	v_cndmask_b32_e64 v248, 0, v248, s[12:13]
	v_cndmask_b32_e64 v249, 0, v249, s[14:15]
	v_cndmask_b32_e64 v250, 0, v250, s[16:17]
	v_cndmask_b32_e64 v251, 0, v251, s[18:19]
	v_add_f32_e32 v162, v242, v243
	v_add_f32_e32 v163, v244, v245
	v_add_f32_e32 v164, v248, v249
	v_add_f32_e32 v165, v250, v251
	v_cvt_pk_bf16_f32 v166, v242, v243
	v_cvt_pk_bf16_f32 v167, v244, v245
	v_cvt_pk_bf16_f32 v168, v248, v249
	v_cvt_pk_bf16_f32 v169, v250, v251
	v_add_f32_e32 v162, v162, v163
	v_add_f32_e32 v164, v164, v165
	v_mfma_f32_16x16x32_bf16 v[2:5], v[114:117], v[166:169], v[2:5]
	v_mfma_f32_16x16x32_bf16 v[6:9], v[118:121], v[166:169], v[6:9]
	v_mfma_f32_16x16x32_bf16 v[10:13], v[122:125], v[166:169], v[10:13]
	v_mfma_f32_16x16x32_bf16 v[14:17], v[126:129], v[166:169], v[14:17]
	v_add_f32_e32 v162, v162, v164
	v_add_f32_e32 v225, v225, v162
.Lattn_skip_a_0:
	s_mul_i32 s96, s94, 1
	s_sub_u32 s96, s92, s96
	s_cmp_lt_u32 s96, 8
	s_cbranch_scc0 .Lattn_skip_a_1
	ds_read2_b32 v[242:243], v215 offset0:62 offset1:63
	ds_read2_b32 v[244:245], v215 offset0:64 offset1:65
	ds_read2_b32 v[248:249], v215 offset0:66 offset1:67
	ds_read2_b32 v[250:251], v215 offset0:68 offset1:69
	v_mfma_f32_16x16x32_bf16 v[162:165], v[98:101], v[74:77], 0
	v_mfma_f32_16x16x32_bf16 v[162:165], v[102:105], v[78:81], v[162:165]
	v_mfma_f32_16x16x32_bf16 v[166:169], v[106:109], v[74:77], 0
	v_mfma_f32_16x16x32_bf16 v[166:169], v[110:113], v[78:81], v[166:169]
	s_waitcnt lgkmcnt(0)
	s_nop 7
	v_add_f32_e32 v242, v162, v242
	v_add_f32_e32 v243, v163, v243
	v_add_f32_e32 v244, v164, v244
	v_add_f32_e32 v245, v165, v245
	v_add_f32_e32 v248, v166, v248
	v_add_f32_e32 v249, v167, v249
	v_add_f32_e32 v250, v168, v250
	v_add_f32_e32 v251, v169, v251
	v_exp_f32_e32 v242, v242
	v_exp_f32_e32 v243, v243
	v_exp_f32_e32 v244, v244
	v_exp_f32_e32 v245, v245
	v_exp_f32_e32 v248, v248
	v_exp_f32_e32 v249, v249
	v_exp_f32_e32 v250, v250
	v_exp_f32_e32 v251, v251
	v_cndmask_b32_e64 v242, 0, v242, s[4:5]
	v_cndmask_b32_e64 v243, 0, v243, s[6:7]
	v_cndmask_b32_e64 v244, 0, v244, s[8:9]
	v_cndmask_b32_e64 v245, 0, v245, s[10:11]
	v_cndmask_b32_e64 v248, 0, v248, s[12:13]
	v_cndmask_b32_e64 v249, 0, v249, s[14:15]
	v_cndmask_b32_e64 v250, 0, v250, s[16:17]
	v_cndmask_b32_e64 v251, 0, v251, s[18:19]
	v_add_f32_e32 v162, v242, v243
	v_add_f32_e32 v163, v244, v245
	v_add_f32_e32 v164, v248, v249
	v_add_f32_e32 v165, v250, v251
	v_cvt_pk_bf16_f32 v166, v242, v243
	v_cvt_pk_bf16_f32 v167, v244, v245
	v_cvt_pk_bf16_f32 v168, v248, v249
	v_cvt_pk_bf16_f32 v169, v250, v251
	v_add_f32_e32 v162, v162, v163
	v_add_f32_e32 v164, v164, v165
	v_mfma_f32_16x16x32_bf16 v[18:21], v[114:117], v[166:169], v[18:21]
	v_mfma_f32_16x16x32_bf16 v[22:25], v[118:121], v[166:169], v[22:25]
	v_mfma_f32_16x16x32_bf16 v[26:29], v[122:125], v[166:169], v[26:29]
	v_mfma_f32_16x16x32_bf16 v[30:33], v[126:129], v[166:169], v[30:33]
	v_add_f32_e32 v162, v162, v164
	v_add_f32_e32 v226, v226, v162
.Lattn_skip_a_1:
	s_mul_i32 s96, s94, 2
	s_sub_u32 s96, s92, s96
	s_cmp_lt_u32 s96, 8
	s_cbranch_scc0 .Lattn_skip_a_2
	ds_read2_b32 v[242:243], v215 offset0:31 offset1:32
	ds_read2_b32 v[244:245], v215 offset0:33 offset1:34
	ds_read2_b32 v[248:249], v215 offset0:35 offset1:36
	ds_read2_b32 v[250:251], v215 offset0:37 offset1:38
	v_mfma_f32_16x16x32_bf16 v[162:165], v[98:101], v[82:85], 0
	v_mfma_f32_16x16x32_bf16 v[162:165], v[102:105], v[86:89], v[162:165]
	v_mfma_f32_16x16x32_bf16 v[166:169], v[106:109], v[82:85], 0
	v_mfma_f32_16x16x32_bf16 v[166:169], v[110:113], v[86:89], v[166:169]
	s_waitcnt lgkmcnt(0)
	s_nop 7
	v_add_f32_e32 v242, v162, v242
	v_add_f32_e32 v243, v163, v243
	v_add_f32_e32 v244, v164, v244
	v_add_f32_e32 v245, v165, v245
	v_add_f32_e32 v248, v166, v248
	v_add_f32_e32 v249, v167, v249
	v_add_f32_e32 v250, v168, v250
	v_add_f32_e32 v251, v169, v251
	v_exp_f32_e32 v242, v242
	v_exp_f32_e32 v243, v243
	v_exp_f32_e32 v244, v244
	v_exp_f32_e32 v245, v245
	v_exp_f32_e32 v248, v248
	v_exp_f32_e32 v249, v249
	v_exp_f32_e32 v250, v250
	v_exp_f32_e32 v251, v251
	v_cndmask_b32_e64 v242, 0, v242, s[4:5]
	v_cndmask_b32_e64 v243, 0, v243, s[6:7]
	v_cndmask_b32_e64 v244, 0, v244, s[8:9]
	v_cndmask_b32_e64 v245, 0, v245, s[10:11]
	v_cndmask_b32_e64 v248, 0, v248, s[12:13]
	v_cndmask_b32_e64 v249, 0, v249, s[14:15]
	v_cndmask_b32_e64 v250, 0, v250, s[16:17]
	v_cndmask_b32_e64 v251, 0, v251, s[18:19]
	v_add_f32_e32 v162, v242, v243
	v_add_f32_e32 v163, v244, v245
	v_add_f32_e32 v164, v248, v249
	v_add_f32_e32 v165, v250, v251
	v_cvt_pk_bf16_f32 v166, v242, v243
	v_cvt_pk_bf16_f32 v167, v244, v245
	v_cvt_pk_bf16_f32 v168, v248, v249
	v_cvt_pk_bf16_f32 v169, v250, v251
	v_add_f32_e32 v162, v162, v163
	v_add_f32_e32 v164, v164, v165
	v_mfma_f32_16x16x32_bf16 v[34:37], v[114:117], v[166:169], v[34:37]
	v_mfma_f32_16x16x32_bf16 v[38:41], v[118:121], v[166:169], v[38:41]
	v_mfma_f32_16x16x32_bf16 v[42:45], v[122:125], v[166:169], v[42:45]
	v_mfma_f32_16x16x32_bf16 v[46:49], v[126:129], v[166:169], v[46:49]
	v_add_f32_e32 v162, v162, v164
	v_add_f32_e32 v227, v227, v162
.Lattn_skip_a_2:
	s_mul_i32 s96, s94, 3
	s_sub_u32 s96, s92, s96
	s_cmp_lt_u32 s96, 8
	s_cbranch_scc0 .Lattn_skip_a_3
	ds_read2_b32 v[242:243], v215 offset0:0 offset1:1
	ds_read2_b32 v[244:245], v215 offset0:2 offset1:3
	ds_read2_b32 v[248:249], v215 offset0:4 offset1:5
	ds_read2_b32 v[250:251], v215 offset0:6 offset1:7
	v_mfma_f32_16x16x32_bf16 v[162:165], v[98:101], v[90:93], 0
	v_mfma_f32_16x16x32_bf16 v[162:165], v[102:105], v[94:97], v[162:165]
	v_mfma_f32_16x16x32_bf16 v[166:169], v[106:109], v[90:93], 0
	v_mfma_f32_16x16x32_bf16 v[166:169], v[110:113], v[94:97], v[166:169]
	s_waitcnt lgkmcnt(0)
	s_nop 7
	v_add_f32_e32 v242, v162, v242
	v_add_f32_e32 v243, v163, v243
	v_add_f32_e32 v244, v164, v244
	v_add_f32_e32 v245, v165, v245
	v_add_f32_e32 v248, v166, v248
	v_add_f32_e32 v249, v167, v249
	v_add_f32_e32 v250, v168, v250
	v_add_f32_e32 v251, v169, v251
	v_exp_f32_e32 v242, v242
	v_exp_f32_e32 v243, v243
	v_exp_f32_e32 v244, v244
	v_exp_f32_e32 v245, v245
	v_exp_f32_e32 v248, v248
	v_exp_f32_e32 v249, v249
	v_exp_f32_e32 v250, v250
	v_exp_f32_e32 v251, v251
	v_cndmask_b32_e64 v242, 0, v242, s[4:5]
	v_cndmask_b32_e64 v243, 0, v243, s[6:7]
	v_cndmask_b32_e64 v244, 0, v244, s[8:9]
	v_cndmask_b32_e64 v245, 0, v245, s[10:11]
	v_cndmask_b32_e64 v248, 0, v248, s[12:13]
	v_cndmask_b32_e64 v249, 0, v249, s[14:15]
	v_cndmask_b32_e64 v250, 0, v250, s[16:17]
	v_cndmask_b32_e64 v251, 0, v251, s[18:19]
	v_add_f32_e32 v162, v242, v243
	v_add_f32_e32 v163, v244, v245
	v_add_f32_e32 v164, v248, v249
	v_add_f32_e32 v165, v250, v251
	v_cvt_pk_bf16_f32 v166, v242, v243
	v_cvt_pk_bf16_f32 v167, v244, v245
	v_cvt_pk_bf16_f32 v168, v248, v249
	v_cvt_pk_bf16_f32 v169, v250, v251
	v_add_f32_e32 v162, v162, v163
	v_add_f32_e32 v164, v164, v165
	v_mfma_f32_16x16x32_bf16 v[50:53], v[114:117], v[166:169], v[50:53]
	v_mfma_f32_16x16x32_bf16 v[54:57], v[118:121], v[166:169], v[54:57]
	v_mfma_f32_16x16x32_bf16 v[58:61], v[122:125], v[166:169], v[58:61]
	v_mfma_f32_16x16x32_bf16 v[62:65], v[126:129], v[166:169], v[62:65]
	v_add_f32_e32 v162, v162, v164
	v_add_f32_e32 v229, v229, v162
.Lattn_skip_a_3:
	v_add_u32_e32 v215, 0x7c, v215
	s_add_u32 s92, s92, 1
	s_cmp_lt_u32 s92, s93
	s_cbranch_scc0 .Lattn_done
	s_add_u32 s95, s92, 2
	s_cmp_lt_u32 s95, s93
	s_cbranch_scc0 .Lattn_nopf2_b
	global_load_dwordx4 v[98:101], v214, s[88:89] offset:-2048
	global_load_dwordx4 v[102:105], v214, s[88:89] offset:-1984
	global_load_dwordx4 v[106:109], v214, s[88:89] offset:2048
	global_load_dwordx4 v[110:113], v214, s[88:89] offset:2112
	global_load_dwordx4 v[114:117], v246, s[90:91]
	global_load_dwordx4 v[118:121], v246, s[98:99]
	global_load_dwordx4 v[122:125], v246, s[100:101]
	global_load_dwordx4 v[126:129], v246, s[52:53]
	s_add_u32 s88, s88, 0x10000
	s_addc_u32 s89, s89, 0
	s_add_u32 s90, s90, 0x80
	s_addc_u32 s91, s91, 0
	s_add_u32 s98, s98, 0x80
	s_addc_u32 s99, s99, 0
	s_add_u32 s100, s100, 0x80
	s_addc_u32 s101, s101, 0
	s_add_u32 s52, s52, 0x80
	s_addc_u32 s53, s53, 0
	s_waitcnt vmcnt(16)
	s_branch .Lattn_go_b

.Lattn_go_b:
	s_cmp_lt_u32 s92, 8
	s_cbranch_scc0 .Lattn_skip_b_0
	ds_read2_b32 v[242:243], v215 offset0:93 offset1:94
	ds_read2_b32 v[244:245], v215 offset0:95 offset1:96
	ds_read2_b32 v[248:249], v215 offset0:97 offset1:98
	ds_read2_b32 v[250:251], v215 offset0:99 offset1:100
	v_mfma_f32_16x16x32_bf16 v[162:165], v[130:133], v[66:69], 0
	v_mfma_f32_16x16x32_bf16 v[162:165], v[134:137], v[70:73], v[162:165]
	v_mfma_f32_16x16x32_bf16 v[166:169], v[138:141], v[66:69], 0
	v_mfma_f32_16x16x32_bf16 v[166:169], v[142:145], v[70:73], v[166:169]
	s_waitcnt lgkmcnt(0)
	s_nop 7
	v_add_f32_e32 v242, v162, v242
	v_add_f32_e32 v243, v163, v243
	v_add_f32_e32 v244, v164, v244
	v_add_f32_e32 v245, v165, v245
	v_add_f32_e32 v248, v166, v248
	v_add_f32_e32 v249, v167, v249
	v_add_f32_e32 v250, v168, v250
	v_add_f32_e32 v251, v169, v251
	v_exp_f32_e32 v242, v242
	v_exp_f32_e32 v243, v243
	v_exp_f32_e32 v244, v244
	v_exp_f32_e32 v245, v245
	v_exp_f32_e32 v248, v248
	v_exp_f32_e32 v249, v249
	v_exp_f32_e32 v250, v250
	v_exp_f32_e32 v251, v251
	v_cndmask_b32_e64 v242, 0, v242, s[4:5]
	v_cndmask_b32_e64 v243, 0, v243, s[6:7]
	v_cndmask_b32_e64 v244, 0, v244, s[8:9]
	v_cndmask_b32_e64 v245, 0, v245, s[10:11]
	v_cndmask_b32_e64 v248, 0, v248, s[12:13]
	v_cndmask_b32_e64 v249, 0, v249, s[14:15]
	v_cndmask_b32_e64 v250, 0, v250, s[16:17]
	v_cndmask_b32_e64 v251, 0, v251, s[18:19]
	v_add_f32_e32 v162, v242, v243
	v_add_f32_e32 v163, v244, v245
	v_add_f32_e32 v164, v248, v249
	v_add_f32_e32 v165, v250, v251
	v_cvt_pk_bf16_f32 v166, v242, v243
	v_cvt_pk_bf16_f32 v167, v244, v245
	v_cvt_pk_bf16_f32 v168, v248, v249
	v_cvt_pk_bf16_f32 v169, v250, v251
	v_add_f32_e32 v162, v162, v163
	v_add_f32_e32 v164, v164, v165
	v_mfma_f32_16x16x32_bf16 v[2:5], v[146:149], v[166:169], v[2:5]
	v_mfma_f32_16x16x32_bf16 v[6:9], v[150:153], v[166:169], v[6:9]
	v_mfma_f32_16x16x32_bf16 v[10:13], v[154:157], v[166:169], v[10:13]
	v_mfma_f32_16x16x32_bf16 v[14:17], v[158:161], v[166:169], v[14:17]
	v_add_f32_e32 v162, v162, v164
	v_add_f32_e32 v225, v225, v162
.Lattn_skip_b_0:
	s_mul_i32 s96, s94, 1
	s_sub_u32 s96, s92, s96
	s_cmp_lt_u32 s96, 8
	s_cbranch_scc0 .Lattn_skip_b_1
	ds_read2_b32 v[242:243], v215 offset0:62 offset1:63
	ds_read2_b32 v[244:245], v215 offset0:64 offset1:65
	ds_read2_b32 v[248:249], v215 offset0:66 offset1:67
	ds_read2_b32 v[250:251], v215 offset0:68 offset1:69
	v_mfma_f32_16x16x32_bf16 v[162:165], v[130:133], v[74:77], 0
	v_mfma_f32_16x16x32_bf16 v[162:165], v[134:137], v[78:81], v[162:165]
	v_mfma_f32_16x16x32_bf16 v[166:169], v[138:141], v[74:77], 0
	v_mfma_f32_16x16x32_bf16 v[166:169], v[142:145], v[78:81], v[166:169]
	s_waitcnt lgkmcnt(0)
	s_nop 7
	v_add_f32_e32 v242, v162, v242
	v_add_f32_e32 v243, v163, v243
	v_add_f32_e32 v244, v164, v244
	v_add_f32_e32 v245, v165, v245
	v_add_f32_e32 v248, v166, v248
	v_add_f32_e32 v249, v167, v249
	v_add_f32_e32 v250, v168, v250
	v_add_f32_e32 v251, v169, v251
	v_exp_f32_e32 v242, v242
	v_exp_f32_e32 v243, v243
	v_exp_f32_e32 v244, v244
	v_exp_f32_e32 v245, v245
	v_exp_f32_e32 v248, v248
	v_exp_f32_e32 v249, v249
	v_exp_f32_e32 v250, v250
	v_exp_f32_e32 v251, v251
	v_cndmask_b32_e64 v242, 0, v242, s[4:5]
	v_cndmask_b32_e64 v243, 0, v243, s[6:7]
	v_cndmask_b32_e64 v244, 0, v244, s[8:9]
	v_cndmask_b32_e64 v245, 0, v245, s[10:11]
	v_cndmask_b32_e64 v248, 0, v248, s[12:13]
	v_cndmask_b32_e64 v249, 0, v249, s[14:15]
	v_cndmask_b32_e64 v250, 0, v250, s[16:17]
	v_cndmask_b32_e64 v251, 0, v251, s[18:19]
	v_add_f32_e32 v162, v242, v243
	v_add_f32_e32 v163, v244, v245
	v_add_f32_e32 v164, v248, v249
	v_add_f32_e32 v165, v250, v251
	v_cvt_pk_bf16_f32 v166, v242, v243
	v_cvt_pk_bf16_f32 v167, v244, v245
	v_cvt_pk_bf16_f32 v168, v248, v249
	v_cvt_pk_bf16_f32 v169, v250, v251
	v_add_f32_e32 v162, v162, v163
	v_add_f32_e32 v164, v164, v165
	v_mfma_f32_16x16x32_bf16 v[18:21], v[146:149], v[166:169], v[18:21]
	v_mfma_f32_16x16x32_bf16 v[22:25], v[150:153], v[166:169], v[22:25]
	v_mfma_f32_16x16x32_bf16 v[26:29], v[154:157], v[166:169], v[26:29]
	v_mfma_f32_16x16x32_bf16 v[30:33], v[158:161], v[166:169], v[30:33]
	v_add_f32_e32 v162, v162, v164
	v_add_f32_e32 v226, v226, v162
.Lattn_skip_b_1:
	s_mul_i32 s96, s94, 2
	s_sub_u32 s96, s92, s96
	s_cmp_lt_u32 s96, 8
	s_cbranch_scc0 .Lattn_skip_b_2
	ds_read2_b32 v[242:243], v215 offset0:31 offset1:32
	ds_read2_b32 v[244:245], v215 offset0:33 offset1:34
	ds_read2_b32 v[248:249], v215 offset0:35 offset1:36
	ds_read2_b32 v[250:251], v215 offset0:37 offset1:38
	v_mfma_f32_16x16x32_bf16 v[162:165], v[130:133], v[82:85], 0
	v_mfma_f32_16x16x32_bf16 v[162:165], v[134:137], v[86:89], v[162:165]
	v_mfma_f32_16x16x32_bf16 v[166:169], v[138:141], v[82:85], 0
	v_mfma_f32_16x16x32_bf16 v[166:169], v[142:145], v[86:89], v[166:169]
	s_waitcnt lgkmcnt(0)
	s_nop 7
	v_add_f32_e32 v242, v162, v242
	v_add_f32_e32 v243, v163, v243
	v_add_f32_e32 v244, v164, v244
	v_add_f32_e32 v245, v165, v245
	v_add_f32_e32 v248, v166, v248
	v_add_f32_e32 v249, v167, v249
	v_add_f32_e32 v250, v168, v250
	v_add_f32_e32 v251, v169, v251
	v_exp_f32_e32 v242, v242
	v_exp_f32_e32 v243, v243
	v_exp_f32_e32 v244, v244
	v_exp_f32_e32 v245, v245
	v_exp_f32_e32 v248, v248
	v_exp_f32_e32 v249, v249
	v_exp_f32_e32 v250, v250
	v_exp_f32_e32 v251, v251
	v_cndmask_b32_e64 v242, 0, v242, s[4:5]
	v_cndmask_b32_e64 v243, 0, v243, s[6:7]
	v_cndmask_b32_e64 v244, 0, v244, s[8:9]
	v_cndmask_b32_e64 v245, 0, v245, s[10:11]
	v_cndmask_b32_e64 v248, 0, v248, s[12:13]
	v_cndmask_b32_e64 v249, 0, v249, s[14:15]
	v_cndmask_b32_e64 v250, 0, v250, s[16:17]
	v_cndmask_b32_e64 v251, 0, v251, s[18:19]
	v_add_f32_e32 v162, v242, v243
	v_add_f32_e32 v163, v244, v245
	v_add_f32_e32 v164, v248, v249
	v_add_f32_e32 v165, v250, v251
	v_cvt_pk_bf16_f32 v166, v242, v243
	v_cvt_pk_bf16_f32 v167, v244, v245
	v_cvt_pk_bf16_f32 v168, v248, v249
	v_cvt_pk_bf16_f32 v169, v250, v251
	v_add_f32_e32 v162, v162, v163
	v_add_f32_e32 v164, v164, v165
	v_mfma_f32_16x16x32_bf16 v[34:37], v[146:149], v[166:169], v[34:37]
	v_mfma_f32_16x16x32_bf16 v[38:41], v[150:153], v[166:169], v[38:41]
	v_mfma_f32_16x16x32_bf16 v[42:45], v[154:157], v[166:169], v[42:45]
	v_mfma_f32_16x16x32_bf16 v[46:49], v[158:161], v[166:169], v[46:49]
	v_add_f32_e32 v162, v162, v164
	v_add_f32_e32 v227, v227, v162
.Lattn_skip_b_2:
	s_mul_i32 s96, s94, 3
	s_sub_u32 s96, s92, s96
	s_cmp_lt_u32 s96, 8
	s_cbranch_scc0 .Lattn_skip_b_3
	ds_read2_b32 v[242:243], v215 offset0:0 offset1:1
	ds_read2_b32 v[244:245], v215 offset0:2 offset1:3
	ds_read2_b32 v[248:249], v215 offset0:4 offset1:5
	ds_read2_b32 v[250:251], v215 offset0:6 offset1:7
	v_mfma_f32_16x16x32_bf16 v[162:165], v[130:133], v[90:93], 0
	v_mfma_f32_16x16x32_bf16 v[162:165], v[134:137], v[94:97], v[162:165]
	v_mfma_f32_16x16x32_bf16 v[166:169], v[138:141], v[90:93], 0
	v_mfma_f32_16x16x32_bf16 v[166:169], v[142:145], v[94:97], v[166:169]
	s_waitcnt lgkmcnt(0)
	s_nop 7
	v_add_f32_e32 v242, v162, v242
	v_add_f32_e32 v243, v163, v243
	v_add_f32_e32 v244, v164, v244
	v_add_f32_e32 v245, v165, v245
	v_add_f32_e32 v248, v166, v248
	v_add_f32_e32 v249, v167, v249
	v_add_f32_e32 v250, v168, v250
	v_add_f32_e32 v251, v169, v251
	v_exp_f32_e32 v242, v242
	v_exp_f32_e32 v243, v243
	v_exp_f32_e32 v244, v244
	v_exp_f32_e32 v245, v245
	v_exp_f32_e32 v248, v248
	v_exp_f32_e32 v249, v249
	v_exp_f32_e32 v250, v250
	v_exp_f32_e32 v251, v251
	v_cndmask_b32_e64 v242, 0, v242, s[4:5]
	v_cndmask_b32_e64 v243, 0, v243, s[6:7]
	v_cndmask_b32_e64 v244, 0, v244, s[8:9]
	v_cndmask_b32_e64 v245, 0, v245, s[10:11]
	v_cndmask_b32_e64 v248, 0, v248, s[12:13]
	v_cndmask_b32_e64 v249, 0, v249, s[14:15]
	v_cndmask_b32_e64 v250, 0, v250, s[16:17]
	v_cndmask_b32_e64 v251, 0, v251, s[18:19]
	v_add_f32_e32 v162, v242, v243
	v_add_f32_e32 v163, v244, v245
	v_add_f32_e32 v164, v248, v249
	v_add_f32_e32 v165, v250, v251
	v_cvt_pk_bf16_f32 v166, v242, v243
	v_cvt_pk_bf16_f32 v167, v244, v245
	v_cvt_pk_bf16_f32 v168, v248, v249
	v_cvt_pk_bf16_f32 v169, v250, v251
	v_add_f32_e32 v162, v162, v163
	v_add_f32_e32 v164, v164, v165
	v_mfma_f32_16x16x32_bf16 v[50:53], v[146:149], v[166:169], v[50:53]
	v_mfma_f32_16x16x32_bf16 v[54:57], v[150:153], v[166:169], v[54:57]
	v_mfma_f32_16x16x32_bf16 v[58:61], v[154:157], v[166:169], v[58:61]
	v_mfma_f32_16x16x32_bf16 v[62:65], v[158:161], v[166:169], v[62:65]
	v_add_f32_e32 v162, v162, v164
	v_add_f32_e32 v229, v229, v162
.Lattn_skip_b_3:
	v_add_u32_e32 v215, 0x7c, v215
	s_add_u32 s92, s92, 1
	s_cmp_lt_u32 s92, s93
	s_cbranch_scc0 .Lattn_done
	s_add_u32 s95, s92, 2
	s_cmp_lt_u32 s95, s93
	s_cbranch_scc0 .Lattn_nopf2_c
	global_load_dwordx4 v[130:133], v214, s[88:89] offset:-2048
	global_load_dwordx4 v[134:137], v214, s[88:89] offset:-1984
	global_load_dwordx4 v[138:141], v214, s[88:89] offset:2048
	global_load_dwordx4 v[142:145], v214, s[88:89] offset:2112
	global_load_dwordx4 v[146:149], v246, s[90:91]
	global_load_dwordx4 v[150:153], v246, s[98:99]
	global_load_dwordx4 v[154:157], v246, s[100:101]
	global_load_dwordx4 v[158:161], v246, s[52:53]
	s_add_u32 s88, s88, 0x10000
	s_addc_u32 s89, s89, 0
	s_add_u32 s90, s90, 0x80
	s_addc_u32 s91, s91, 0
	s_add_u32 s98, s98, 0x80
	s_addc_u32 s99, s99, 0
	s_add_u32 s100, s100, 0x80
	s_addc_u32 s101, s101, 0
	s_add_u32 s52, s52, 0x80
	s_addc_u32 s53, s53, 0
	s_waitcnt vmcnt(16)
	s_branch .Lattn_go_c

.Lattn_go_c:
	s_cmp_lt_u32 s92, 8
	s_cbranch_scc0 .Lattn_skip_c_0
	ds_read2_b32 v[242:243], v215 offset0:93 offset1:94
	ds_read2_b32 v[244:245], v215 offset0:95 offset1:96
	ds_read2_b32 v[248:249], v215 offset0:97 offset1:98
	ds_read2_b32 v[250:251], v215 offset0:99 offset1:100
	v_mfma_f32_16x16x32_bf16 v[162:165], v[194:197], v[66:69], 0
	v_mfma_f32_16x16x32_bf16 v[162:165], v[198:201], v[70:73], v[162:165]
	v_mfma_f32_16x16x32_bf16 v[166:169], v[202:205], v[66:69], 0
	v_mfma_f32_16x16x32_bf16 v[166:169], v[206:209], v[70:73], v[166:169]
	s_waitcnt lgkmcnt(0)
	s_nop 7
	v_add_f32_e32 v242, v162, v242
	v_add_f32_e32 v243, v163, v243
	v_add_f32_e32 v244, v164, v244
	v_add_f32_e32 v245, v165, v245
	v_add_f32_e32 v248, v166, v248
	v_add_f32_e32 v249, v167, v249
	v_add_f32_e32 v250, v168, v250
	v_add_f32_e32 v251, v169, v251
	v_exp_f32_e32 v242, v242
	v_exp_f32_e32 v243, v243
	v_exp_f32_e32 v244, v244
	v_exp_f32_e32 v245, v245
	v_exp_f32_e32 v248, v248
	v_exp_f32_e32 v249, v249
	v_exp_f32_e32 v250, v250
	v_exp_f32_e32 v251, v251
	v_cndmask_b32_e64 v242, 0, v242, s[4:5]
	v_cndmask_b32_e64 v243, 0, v243, s[6:7]
	v_cndmask_b32_e64 v244, 0, v244, s[8:9]
	v_cndmask_b32_e64 v245, 0, v245, s[10:11]
	v_cndmask_b32_e64 v248, 0, v248, s[12:13]
	v_cndmask_b32_e64 v249, 0, v249, s[14:15]
	v_cndmask_b32_e64 v250, 0, v250, s[16:17]
	v_cndmask_b32_e64 v251, 0, v251, s[18:19]
	v_add_f32_e32 v162, v242, v243
	v_add_f32_e32 v163, v244, v245
	v_add_f32_e32 v164, v248, v249
	v_add_f32_e32 v165, v250, v251
	v_cvt_pk_bf16_f32 v166, v242, v243
	v_cvt_pk_bf16_f32 v167, v244, v245
	v_cvt_pk_bf16_f32 v168, v248, v249
	v_cvt_pk_bf16_f32 v169, v250, v251
	v_add_f32_e32 v162, v162, v163
	v_add_f32_e32 v164, v164, v165
	v_mfma_f32_16x16x32_bf16 v[2:5], v[210:213], v[166:169], v[2:5]
	v_mfma_f32_16x16x32_bf16 v[6:9], v[230:233], v[166:169], v[6:9]
	v_mfma_f32_16x16x32_bf16 v[10:13], v[234:237], v[166:169], v[10:13]
	v_mfma_f32_16x16x32_bf16 v[14:17], v[238:241], v[166:169], v[14:17]
	v_add_f32_e32 v162, v162, v164
	v_add_f32_e32 v225, v225, v162
.Lattn_skip_c_0:
	s_mul_i32 s96, s94, 1
	s_sub_u32 s96, s92, s96
	s_cmp_lt_u32 s96, 8
	s_cbranch_scc0 .Lattn_skip_c_1
	ds_read2_b32 v[242:243], v215 offset0:62 offset1:63
	ds_read2_b32 v[244:245], v215 offset0:64 offset1:65
	ds_read2_b32 v[248:249], v215 offset0:66 offset1:67
	ds_read2_b32 v[250:251], v215 offset0:68 offset1:69
	v_mfma_f32_16x16x32_bf16 v[162:165], v[194:197], v[74:77], 0
	v_mfma_f32_16x16x32_bf16 v[162:165], v[198:201], v[78:81], v[162:165]
	v_mfma_f32_16x16x32_bf16 v[166:169], v[202:205], v[74:77], 0
	v_mfma_f32_16x16x32_bf16 v[166:169], v[206:209], v[78:81], v[166:169]
	s_waitcnt lgkmcnt(0)
	s_nop 7
	v_add_f32_e32 v242, v162, v242
	v_add_f32_e32 v243, v163, v243
	v_add_f32_e32 v244, v164, v244
	v_add_f32_e32 v245, v165, v245
	v_add_f32_e32 v248, v166, v248
	v_add_f32_e32 v249, v167, v249
	v_add_f32_e32 v250, v168, v250
	v_add_f32_e32 v251, v169, v251
	v_exp_f32_e32 v242, v242
	v_exp_f32_e32 v243, v243
	v_exp_f32_e32 v244, v244
	v_exp_f32_e32 v245, v245
	v_exp_f32_e32 v248, v248
	v_exp_f32_e32 v249, v249
	v_exp_f32_e32 v250, v250
	v_exp_f32_e32 v251, v251
	v_cndmask_b32_e64 v242, 0, v242, s[4:5]
	v_cndmask_b32_e64 v243, 0, v243, s[6:7]
	v_cndmask_b32_e64 v244, 0, v244, s[8:9]
	v_cndmask_b32_e64 v245, 0, v245, s[10:11]
	v_cndmask_b32_e64 v248, 0, v248, s[12:13]
	v_cndmask_b32_e64 v249, 0, v249, s[14:15]
	v_cndmask_b32_e64 v250, 0, v250, s[16:17]
	v_cndmask_b32_e64 v251, 0, v251, s[18:19]
	v_add_f32_e32 v162, v242, v243
	v_add_f32_e32 v163, v244, v245
	v_add_f32_e32 v164, v248, v249
	v_add_f32_e32 v165, v250, v251
	v_cvt_pk_bf16_f32 v166, v242, v243
	v_cvt_pk_bf16_f32 v167, v244, v245
	v_cvt_pk_bf16_f32 v168, v248, v249
	v_cvt_pk_bf16_f32 v169, v250, v251
	v_add_f32_e32 v162, v162, v163
	v_add_f32_e32 v164, v164, v165
	v_mfma_f32_16x16x32_bf16 v[18:21], v[210:213], v[166:169], v[18:21]
	v_mfma_f32_16x16x32_bf16 v[22:25], v[230:233], v[166:169], v[22:25]
	v_mfma_f32_16x16x32_bf16 v[26:29], v[234:237], v[166:169], v[26:29]
	v_mfma_f32_16x16x32_bf16 v[30:33], v[238:241], v[166:169], v[30:33]
	v_add_f32_e32 v162, v162, v164
	v_add_f32_e32 v226, v226, v162
.Lattn_skip_c_1:
	s_mul_i32 s96, s94, 2
	s_sub_u32 s96, s92, s96
	s_cmp_lt_u32 s96, 8
	s_cbranch_scc0 .Lattn_skip_c_2
	ds_read2_b32 v[242:243], v215 offset0:31 offset1:32
	ds_read2_b32 v[244:245], v215 offset0:33 offset1:34
	ds_read2_b32 v[248:249], v215 offset0:35 offset1:36
	ds_read2_b32 v[250:251], v215 offset0:37 offset1:38
	v_mfma_f32_16x16x32_bf16 v[162:165], v[194:197], v[82:85], 0
	v_mfma_f32_16x16x32_bf16 v[162:165], v[198:201], v[86:89], v[162:165]
	v_mfma_f32_16x16x32_bf16 v[166:169], v[202:205], v[82:85], 0
	v_mfma_f32_16x16x32_bf16 v[166:169], v[206:209], v[86:89], v[166:169]
	s_waitcnt lgkmcnt(0)
	s_nop 7
	v_add_f32_e32 v242, v162, v242
	v_add_f32_e32 v243, v163, v243
	v_add_f32_e32 v244, v164, v244
	v_add_f32_e32 v245, v165, v245
	v_add_f32_e32 v248, v166, v248
	v_add_f32_e32 v249, v167, v249
	v_add_f32_e32 v250, v168, v250
	v_add_f32_e32 v251, v169, v251
	v_exp_f32_e32 v242, v242
	v_exp_f32_e32 v243, v243
	v_exp_f32_e32 v244, v244
	v_exp_f32_e32 v245, v245
	v_exp_f32_e32 v248, v248
	v_exp_f32_e32 v249, v249
	v_exp_f32_e32 v250, v250
	v_exp_f32_e32 v251, v251
	v_cndmask_b32_e64 v242, 0, v242, s[4:5]
	v_cndmask_b32_e64 v243, 0, v243, s[6:7]
	v_cndmask_b32_e64 v244, 0, v244, s[8:9]
	v_cndmask_b32_e64 v245, 0, v245, s[10:11]
	v_cndmask_b32_e64 v248, 0, v248, s[12:13]
	v_cndmask_b32_e64 v249, 0, v249, s[14:15]
	v_cndmask_b32_e64 v250, 0, v250, s[16:17]
	v_cndmask_b32_e64 v251, 0, v251, s[18:19]
	v_add_f32_e32 v162, v242, v243
	v_add_f32_e32 v163, v244, v245
	v_add_f32_e32 v164, v248, v249
	v_add_f32_e32 v165, v250, v251
	v_cvt_pk_bf16_f32 v166, v242, v243
	v_cvt_pk_bf16_f32 v167, v244, v245
	v_cvt_pk_bf16_f32 v168, v248, v249
	v_cvt_pk_bf16_f32 v169, v250, v251
	v_add_f32_e32 v162, v162, v163
	v_add_f32_e32 v164, v164, v165
	v_mfma_f32_16x16x32_bf16 v[34:37], v[210:213], v[166:169], v[34:37]
	v_mfma_f32_16x16x32_bf16 v[38:41], v[230:233], v[166:169], v[38:41]
	v_mfma_f32_16x16x32_bf16 v[42:45], v[234:237], v[166:169], v[42:45]
	v_mfma_f32_16x16x32_bf16 v[46:49], v[238:241], v[166:169], v[46:49]
	v_add_f32_e32 v162, v162, v164
	v_add_f32_e32 v227, v227, v162
.Lattn_skip_c_2:
	s_mul_i32 s96, s94, 3
	s_sub_u32 s96, s92, s96
	s_cmp_lt_u32 s96, 8
	s_cbranch_scc0 .Lattn_skip_c_3
	ds_read2_b32 v[242:243], v215 offset0:0 offset1:1
	ds_read2_b32 v[244:245], v215 offset0:2 offset1:3
	ds_read2_b32 v[248:249], v215 offset0:4 offset1:5
	ds_read2_b32 v[250:251], v215 offset0:6 offset1:7
	v_mfma_f32_16x16x32_bf16 v[162:165], v[194:197], v[90:93], 0
	v_mfma_f32_16x16x32_bf16 v[162:165], v[198:201], v[94:97], v[162:165]
	v_mfma_f32_16x16x32_bf16 v[166:169], v[202:205], v[90:93], 0
	v_mfma_f32_16x16x32_bf16 v[166:169], v[206:209], v[94:97], v[166:169]
	s_waitcnt lgkmcnt(0)
	s_nop 7
	v_add_f32_e32 v242, v162, v242
	v_add_f32_e32 v243, v163, v243
	v_add_f32_e32 v244, v164, v244
	v_add_f32_e32 v245, v165, v245
	v_add_f32_e32 v248, v166, v248
	v_add_f32_e32 v249, v167, v249
	v_add_f32_e32 v250, v168, v250
	v_add_f32_e32 v251, v169, v251
	v_exp_f32_e32 v242, v242
	v_exp_f32_e32 v243, v243
	v_exp_f32_e32 v244, v244
	v_exp_f32_e32 v245, v245
	v_exp_f32_e32 v248, v248
	v_exp_f32_e32 v249, v249
	v_exp_f32_e32 v250, v250
	v_exp_f32_e32 v251, v251
	v_cndmask_b32_e64 v242, 0, v242, s[4:5]
	v_cndmask_b32_e64 v243, 0, v243, s[6:7]
	v_cndmask_b32_e64 v244, 0, v244, s[8:9]
	v_cndmask_b32_e64 v245, 0, v245, s[10:11]
	v_cndmask_b32_e64 v248, 0, v248, s[12:13]
	v_cndmask_b32_e64 v249, 0, v249, s[14:15]
	v_cndmask_b32_e64 v250, 0, v250, s[16:17]
	v_cndmask_b32_e64 v251, 0, v251, s[18:19]
	v_add_f32_e32 v162, v242, v243
	v_add_f32_e32 v163, v244, v245
	v_add_f32_e32 v164, v248, v249
	v_add_f32_e32 v165, v250, v251
	v_cvt_pk_bf16_f32 v166, v242, v243
	v_cvt_pk_bf16_f32 v167, v244, v245
	v_cvt_pk_bf16_f32 v168, v248, v249
	v_cvt_pk_bf16_f32 v169, v250, v251
	v_add_f32_e32 v162, v162, v163
	v_add_f32_e32 v164, v164, v165
	v_mfma_f32_16x16x32_bf16 v[50:53], v[210:213], v[166:169], v[50:53]
	v_mfma_f32_16x16x32_bf16 v[54:57], v[230:233], v[166:169], v[54:57]
	v_mfma_f32_16x16x32_bf16 v[58:61], v[234:237], v[166:169], v[58:61]
	v_mfma_f32_16x16x32_bf16 v[62:65], v[238:241], v[166:169], v[62:65]
	v_add_f32_e32 v162, v162, v164
	v_add_f32_e32 v229, v229, v162
.Lattn_skip_c_3:
	v_add_u32_e32 v215, 0x7c, v215
	s_add_u32 s92, s92, 1
	s_cmp_lt_u32 s92, s93
	s_cbranch_scc1 .Lattn_loop
.Lattn_done:
	global_load_dwordx4 v[98:101], v[192:193], off offset:0
	global_load_dwordx4 v[102:105], v[192:193], off offset:64
	global_load_dwordx4 v[106:109], v[192:193], off offset:128
	global_load_dwordx4 v[110:113], v[192:193], off offset:192
	v_mbcnt_lo_u32_b32 v246, -1, 0
	v_mbcnt_hi_u32_b32 v246, -1, v246
	v_lshlrev_b32_e32 v246, 4, v246
	global_load_dwordx4 v[194:197], v[182:183], off
	global_load_dwordx4 v[198:201], v[182:183], off offset:16
	global_load_dwordx4 v[202:205], v[182:183], off offset:2048
	global_load_dwordx4 v[206:209], v[182:183], off offset:2064
	global_load_dwordx4 v[210:213], v[184:185], off
	global_load_dwordx4 v[230:233], v[184:185], off offset:16
	global_load_dwordx4 v[234:237], v[186:187], off
	global_load_dwordx4 v[238:241], v[186:187], off offset:16
	s_add_u32 s81, s79, s78
	s_lshl_b32 s81, s81, 6
	s_add_u32 s81, s81, s69
	s_add_u32 s51, s81, s46
	s_lshl_b32 s51, s51, 11
	s_add_u32 s90, s30, 0x1d000000
	s_addc_u32 s91, s31, 0
	s_add_u32 s90, s90, s51
	s_addc_u32 s91, s91, 0
	global_load_dwordx4 v[130:133], v246, s[90:91] offset:-1024
	global_load_dwordx4 v[134:137], v246, s[90:91] offset:1024
	global_load_dwordx4 v[138:141], v246, s[90:91] offset:3072
	global_load_dwordx4 v[66:69], v246, s[90:91]
	global_load_dwordx4 v[70:73], v246, s[90:91] offset:2048
	s_add_u32 s90, s90, 0x1000
	s_addc_u32 s91, s91, 0
	global_load_dwordx4 v[142:145], v246, s[90:91] offset:1024
	global_load_dwordx4 v[146:149], v246, s[90:91] offset:3072
	global_load_dwordx4 v[74:77], v246, s[90:91]
	global_load_dwordx4 v[78:81], v246, s[90:91] offset:2048
	s_add_u32 s90, s90, 0x1000
	s_addc_u32 s91, s91, 0
	global_load_dwordx4 v[150:153], v246, s[90:91] offset:1024
	global_load_dwordx4 v[154:157], v246, s[90:91] offset:3072
	global_load_dwordx4 v[82:85], v246, s[90:91]
	global_load_dwordx4 v[86:89], v246, s[90:91] offset:2048
	s_add_u32 s90, s90, 0x1000
	s_addc_u32 s91, s91, 0
	global_load_dwordx4 v[158:161], v246, s[90:91] offset:1024
	global_load_dwordx4 v[162:165], v246, s[90:91] offset:3072
	global_load_dwordx4 v[90:93], v246, s[90:91]
	global_load_dwordx4 v[94:97], v246, s[90:91] offset:2048
	s_add_u32 s90, s90, 0x1000
	s_addc_u32 s91, s91, 0
	global_load_dwordx4 v[166:169], v246, s[90:91] offset:1024
	v_mbcnt_lo_u32_b32 v126, -1, 0
	v_mbcnt_hi_u32_b32 v126, -1, v126
	v_and_b32_e32 v127, 15, v126
	v_lshrrev_b32_e32 v128, 4, v126
	v_xor_b32_e32 v114, 16, v126
	v_lshlrev_b32_e32 v114, 2, v114
	v_xor_b32_e32 v115, 32, v126
	v_lshlrev_b32_e32 v115, 2, v115
	v_lshl_add_u32 v129, s67, 4, v127
	v_lshlrev_b32_e32 v116, 11, v129
	v_lshl_add_u32 v116, v128, 3, v116
	s_lshl_b32 s51, s79, 6
	s_add_u32 s51, s51, s46
	s_lshl_b32 s51, s51, 11
	s_lshl_b32 s54, s83, 7
	s_add_u32 s51, s51, s54
	s_add_u32 s88, s30, 0x2c000000
	s_addc_u32 s89, s31, 0
	s_add_u32 s88, s88, s51
	s_addc_u32 s89, s89, 0
	ds_bpermute_b32 v118, v114, v225
	ds_bpermute_b32 v119, v114, v226
	ds_bpermute_b32 v120, v114, v227
	ds_bpermute_b32 v121, v114, v229
	s_waitcnt lgkmcnt(0)
	v_add_f32_e32 v225, v225, v118
	v_add_f32_e32 v226, v226, v119
	v_add_f32_e32 v227, v227, v120
	v_add_f32_e32 v229, v229, v121
	ds_bpermute_b32 v118, v115, v225
	ds_bpermute_b32 v119, v115, v226
	ds_bpermute_b32 v120, v115, v227
	ds_bpermute_b32 v121, v115, v229
	s_waitcnt lgkmcnt(0)
	v_add_f32_e32 v225, v225, v118
	v_add_f32_e32 v226, v226, v119
	v_add_f32_e32 v227, v227, v120
	v_add_f32_e32 v229, v229, v121
	v_rcp_f32_e32 v225, v225
	v_rcp_f32_e32 v226, v226
	v_rcp_f32_e32 v227, v227
	v_rcp_f32_e32 v229, v229
	s_nop 0
	v_mul_f32_e32 v2, v2, v225
	v_mul_f32_e32 v3, v3, v225
	v_mul_f32_e32 v4, v4, v225
	v_mul_f32_e32 v5, v5, v225
	v_mul_f32_e32 v6, v6, v225
	v_mul_f32_e32 v7, v7, v225
	v_mul_f32_e32 v8, v8, v225
	v_mul_f32_e32 v9, v9, v225
	v_mul_f32_e32 v10, v10, v225
	v_mul_f32_e32 v11, v11, v225
	v_mul_f32_e32 v12, v12, v225
	v_mul_f32_e32 v13, v13, v225
	v_mul_f32_e32 v14, v14, v225
	v_mul_f32_e32 v15, v15, v225
	v_mul_f32_e32 v16, v16, v225
	v_mul_f32_e32 v17, v17, v225
	v_mul_f32_e32 v18, v18, v226
	v_mul_f32_e32 v19, v19, v226
	v_mul_f32_e32 v20, v20, v226
	v_mul_f32_e32 v21, v21, v226
	v_mul_f32_e32 v22, v22, v226
	v_mul_f32_e32 v23, v23, v226
	v_mul_f32_e32 v24, v24, v226
	v_mul_f32_e32 v25, v25, v226
	v_mul_f32_e32 v26, v26, v226
	v_mul_f32_e32 v27, v27, v226
	v_mul_f32_e32 v28, v28, v226
	v_mul_f32_e32 v29, v29, v226
	v_mul_f32_e32 v30, v30, v226
	v_mul_f32_e32 v31, v31, v226
	v_mul_f32_e32 v32, v32, v226
	v_mul_f32_e32 v33, v33, v226
	v_mul_f32_e32 v34, v34, v227
	v_mul_f32_e32 v35, v35, v227
	v_mul_f32_e32 v36, v36, v227
	v_mul_f32_e32 v37, v37, v227
	v_mul_f32_e32 v38, v38, v227
	v_mul_f32_e32 v39, v39, v227
	v_mul_f32_e32 v40, v40, v227
	v_mul_f32_e32 v41, v41, v227
	v_mul_f32_e32 v42, v42, v227
	v_mul_f32_e32 v43, v43, v227
	v_mul_f32_e32 v44, v44, v227
	v_mul_f32_e32 v45, v45, v227
	v_mul_f32_e32 v46, v46, v227
	v_mul_f32_e32 v47, v47, v227
	v_mul_f32_e32 v48, v48, v227
	v_mul_f32_e32 v49, v49, v227
	v_mul_f32_e32 v50, v50, v229
	v_mul_f32_e32 v51, v51, v229
	v_mul_f32_e32 v52, v52, v229
	v_mul_f32_e32 v53, v53, v229
	v_mul_f32_e32 v54, v54, v229
	v_mul_f32_e32 v55, v55, v229
	v_mul_f32_e32 v56, v56, v229
	v_mul_f32_e32 v57, v57, v229
	v_mul_f32_e32 v58, v58, v229
	v_mul_f32_e32 v59, v59, v229
	v_mul_f32_e32 v60, v60, v229
	v_mul_f32_e32 v61, v61, v229
	v_mul_f32_e32 v62, v62, v229
	v_mul_f32_e32 v63, v63, v229
	v_mul_f32_e32 v64, v64, v229
	v_mul_f32_e32 v65, v65, v229
	v_mul_f32_e32 v118, v2, v2
	v_fmac_f32_e32 v118, v3, v3
	v_fmac_f32_e32 v118, v4, v4
	v_fmac_f32_e32 v118, v5, v5
	v_fmac_f32_e32 v118, v6, v6
	v_fmac_f32_e32 v118, v7, v7
	v_fmac_f32_e32 v118, v8, v8
	v_fmac_f32_e32 v118, v9, v9
	v_fmac_f32_e32 v118, v10, v10
	v_fmac_f32_e32 v118, v11, v11
	v_fmac_f32_e32 v118, v12, v12
	v_fmac_f32_e32 v118, v13, v13
	v_fmac_f32_e32 v118, v14, v14
	v_fmac_f32_e32 v118, v15, v15
	v_fmac_f32_e32 v118, v16, v16
	v_fmac_f32_e32 v118, v17, v17
	v_mul_f32_e32 v119, v18, v18
	v_fmac_f32_e32 v119, v19, v19
	v_fmac_f32_e32 v119, v20, v20
	v_fmac_f32_e32 v119, v21, v21
	v_fmac_f32_e32 v119, v22, v22
	v_fmac_f32_e32 v119, v23, v23
	v_fmac_f32_e32 v119, v24, v24
	v_fmac_f32_e32 v119, v25, v25
	v_fmac_f32_e32 v119, v26, v26
	v_fmac_f32_e32 v119, v27, v27
	v_fmac_f32_e32 v119, v28, v28
	v_fmac_f32_e32 v119, v29, v29
	v_fmac_f32_e32 v119, v30, v30
	v_fmac_f32_e32 v119, v31, v31
	v_fmac_f32_e32 v119, v32, v32
	v_fmac_f32_e32 v119, v33, v33
	v_mul_f32_e32 v120, v34, v34
	v_fmac_f32_e32 v120, v35, v35
	v_fmac_f32_e32 v120, v36, v36
	v_fmac_f32_e32 v120, v37, v37
	v_fmac_f32_e32 v120, v38, v38
	v_fmac_f32_e32 v120, v39, v39
	v_fmac_f32_e32 v120, v40, v40
	v_fmac_f32_e32 v120, v41, v41
	v_fmac_f32_e32 v120, v42, v42
	v_fmac_f32_e32 v120, v43, v43
	v_fmac_f32_e32 v120, v44, v44
	v_fmac_f32_e32 v120, v45, v45
	v_fmac_f32_e32 v120, v46, v46
	v_fmac_f32_e32 v120, v47, v47
	v_fmac_f32_e32 v120, v48, v48
	v_fmac_f32_e32 v120, v49, v49
	v_mul_f32_e32 v121, v50, v50
	v_fmac_f32_e32 v121, v51, v51
	v_fmac_f32_e32 v121, v52, v52
	v_fmac_f32_e32 v121, v53, v53
	v_fmac_f32_e32 v121, v54, v54
	v_fmac_f32_e32 v121, v55, v55
	v_fmac_f32_e32 v121, v56, v56
	v_fmac_f32_e32 v121, v57, v57
	v_fmac_f32_e32 v121, v58, v58
	v_fmac_f32_e32 v121, v59, v59
	v_fmac_f32_e32 v121, v60, v60
	v_fmac_f32_e32 v121, v61, v61
	v_fmac_f32_e32 v121, v62, v62
	v_fmac_f32_e32 v121, v63, v63
	v_fmac_f32_e32 v121, v64, v64
	v_fmac_f32_e32 v121, v65, v65
	ds_bpermute_b32 v122, v114, v118
	ds_bpermute_b32 v123, v114, v119
	ds_bpermute_b32 v124, v114, v120
	ds_bpermute_b32 v125, v114, v121
	s_waitcnt lgkmcnt(0)
	v_add_f32_e32 v118, v118, v122
	v_add_f32_e32 v119, v119, v123
	v_add_f32_e32 v120, v120, v124
	v_add_f32_e32 v121, v121, v125
	ds_bpermute_b32 v122, v115, v118
	ds_bpermute_b32 v123, v115, v119
	ds_bpermute_b32 v124, v115, v120
	ds_bpermute_b32 v125, v115, v121
	s_waitcnt lgkmcnt(0)
	v_add_f32_e32 v118, v118, v122
	v_add_f32_e32 v119, v119, v123
	v_add_f32_e32 v120, v120, v124
	v_add_f32_e32 v121, v121, v125
	v_fmamk_f32 v118, v118, 0x3c800000, v224
	v_fmamk_f32 v119, v119, 0x3c800000, v224
	v_fmamk_f32 v120, v120, 0x3c800000, v224
	v_fmamk_f32 v121, v121, 0x3c800000, v224
	v_rsq_f32_e32 v118, v118
	v_rsq_f32_e32 v119, v119
	v_rsq_f32_e32 v120, v120
	v_rsq_f32_e32 v121, v121
	s_waitcnt vmcnt(26)
	v_mul_f32_e32 v2, v2, v118
	v_mul_f32_e32 v3, v3, v118
	v_mul_f32_e32 v4, v4, v118
	v_mul_f32_e32 v5, v5, v118
	v_mul_f32_e32 v2, v2, v98
	v_mul_f32_e32 v3, v3, v99
	v_mul_f32_e32 v4, v4, v100
	v_mul_f32_e32 v5, v5, v101
	v_cvt_pk_bf16_f32 v2, v2, v3
	v_cvt_pk_bf16_f32 v3, v4, v5
	global_store_dwordx2 v116, v[2:3], s[88:89] offset:0
	v_mul_f32_e32 v6, v6, v118
	v_mul_f32_e32 v7, v7, v118
	v_mul_f32_e32 v8, v8, v118
	v_mul_f32_e32 v9, v9, v118
	v_mul_f32_e32 v6, v6, v102
	v_mul_f32_e32 v7, v7, v103
	v_mul_f32_e32 v8, v8, v104
	v_mul_f32_e32 v9, v9, v105
	v_cvt_pk_bf16_f32 v6, v6, v7
	v_cvt_pk_bf16_f32 v7, v8, v9
	global_store_dwordx2 v116, v[6:7], s[88:89] offset:32
	v_mul_f32_e32 v10, v10, v118
	v_mul_f32_e32 v11, v11, v118
	v_mul_f32_e32 v12, v12, v118
	v_mul_f32_e32 v13, v13, v118
	v_mul_f32_e32 v10, v10, v106
	v_mul_f32_e32 v11, v11, v107
	v_mul_f32_e32 v12, v12, v108
	v_mul_f32_e32 v13, v13, v109
	v_cvt_pk_bf16_f32 v10, v10, v11
	v_cvt_pk_bf16_f32 v11, v12, v13
	global_store_dwordx2 v116, v[10:11], s[88:89] offset:64
	v_mul_f32_e32 v14, v14, v118
	v_mul_f32_e32 v15, v15, v118
	v_mul_f32_e32 v16, v16, v118
	v_mul_f32_e32 v17, v17, v118
	v_mul_f32_e32 v14, v14, v110
	v_mul_f32_e32 v15, v15, v111
	v_mul_f32_e32 v16, v16, v112
	v_mul_f32_e32 v17, v17, v113
	v_cvt_pk_bf16_f32 v14, v14, v15
	v_cvt_pk_bf16_f32 v15, v16, v17
	global_store_dwordx2 v116, v[14:15], s[88:89] offset:96
	s_add_u32 s88, s88, 0x20000
	s_addc_u32 s89, s89, 0
	v_mul_f32_e32 v18, v18, v119
	v_mul_f32_e32 v19, v19, v119
	v_mul_f32_e32 v20, v20, v119
	v_mul_f32_e32 v21, v21, v119
	v_mul_f32_e32 v18, v18, v98
	v_mul_f32_e32 v19, v19, v99
	v_mul_f32_e32 v20, v20, v100
	v_mul_f32_e32 v21, v21, v101
	v_cvt_pk_bf16_f32 v18, v18, v19
	v_cvt_pk_bf16_f32 v19, v20, v21
	global_store_dwordx2 v116, v[18:19], s[88:89] offset:0
	v_mul_f32_e32 v22, v22, v119
	v_mul_f32_e32 v23, v23, v119
	v_mul_f32_e32 v24, v24, v119
	v_mul_f32_e32 v25, v25, v119
	v_mul_f32_e32 v22, v22, v102
	v_mul_f32_e32 v23, v23, v103
	v_mul_f32_e32 v24, v24, v104
	v_mul_f32_e32 v25, v25, v105
	v_cvt_pk_bf16_f32 v22, v22, v23
	v_cvt_pk_bf16_f32 v23, v24, v25
	global_store_dwordx2 v116, v[22:23], s[88:89] offset:32
	v_mul_f32_e32 v26, v26, v119
	v_mul_f32_e32 v27, v27, v119
	v_mul_f32_e32 v28, v28, v119
	v_mul_f32_e32 v29, v29, v119
	v_mul_f32_e32 v26, v26, v106
	v_mul_f32_e32 v27, v27, v107
	v_mul_f32_e32 v28, v28, v108
	v_mul_f32_e32 v29, v29, v109
	v_cvt_pk_bf16_f32 v26, v26, v27
	v_cvt_pk_bf16_f32 v27, v28, v29
	global_store_dwordx2 v116, v[26:27], s[88:89] offset:64
	v_mul_f32_e32 v30, v30, v119
	v_mul_f32_e32 v31, v31, v119
	v_mul_f32_e32 v32, v32, v119
	v_mul_f32_e32 v33, v33, v119
	v_mul_f32_e32 v30, v30, v110
	v_mul_f32_e32 v31, v31, v111
	v_mul_f32_e32 v32, v32, v112
	v_mul_f32_e32 v33, v33, v113
	v_cvt_pk_bf16_f32 v30, v30, v31
	v_cvt_pk_bf16_f32 v31, v32, v33
	global_store_dwordx2 v116, v[30:31], s[88:89] offset:96
	s_add_u32 s88, s88, 0x20000
	s_addc_u32 s89, s89, 0
	v_mul_f32_e32 v34, v34, v120
	v_mul_f32_e32 v35, v35, v120
	v_mul_f32_e32 v36, v36, v120
	v_mul_f32_e32 v37, v37, v120
	v_mul_f32_e32 v34, v34, v98
	v_mul_f32_e32 v35, v35, v99
	v_mul_f32_e32 v36, v36, v100
	v_mul_f32_e32 v37, v37, v101
	v_cvt_pk_bf16_f32 v34, v34, v35
	v_cvt_pk_bf16_f32 v35, v36, v37
	global_store_dwordx2 v116, v[34:35], s[88:89] offset:0
	v_mul_f32_e32 v38, v38, v120
	v_mul_f32_e32 v39, v39, v120
	v_mul_f32_e32 v40, v40, v120
	v_mul_f32_e32 v41, v41, v120
	v_mul_f32_e32 v38, v38, v102
	v_mul_f32_e32 v39, v39, v103
	v_mul_f32_e32 v40, v40, v104
	v_mul_f32_e32 v41, v41, v105
	v_cvt_pk_bf16_f32 v38, v38, v39
	v_cvt_pk_bf16_f32 v39, v40, v41
	global_store_dwordx2 v116, v[38:39], s[88:89] offset:32
	v_mul_f32_e32 v42, v42, v120
	v_mul_f32_e32 v43, v43, v120
	v_mul_f32_e32 v44, v44, v120
	v_mul_f32_e32 v45, v45, v120
	v_mul_f32_e32 v42, v42, v106
	v_mul_f32_e32 v43, v43, v107
	v_mul_f32_e32 v44, v44, v108
	v_mul_f32_e32 v45, v45, v109
	v_cvt_pk_bf16_f32 v42, v42, v43
	v_cvt_pk_bf16_f32 v43, v44, v45
	global_store_dwordx2 v116, v[42:43], s[88:89] offset:64
	v_mul_f32_e32 v46, v46, v120
	v_mul_f32_e32 v47, v47, v120
	v_mul_f32_e32 v48, v48, v120
	v_mul_f32_e32 v49, v49, v120
	v_mul_f32_e32 v46, v46, v110
	v_mul_f32_e32 v47, v47, v111
	v_mul_f32_e32 v48, v48, v112
	v_mul_f32_e32 v49, v49, v113
	v_cvt_pk_bf16_f32 v46, v46, v47
	v_cvt_pk_bf16_f32 v47, v48, v49
	global_store_dwordx2 v116, v[46:47], s[88:89] offset:96
	s_add_u32 s88, s88, 0x20000
	s_addc_u32 s89, s89, 0
	v_mul_f32_e32 v50, v50, v121
	v_mul_f32_e32 v51, v51, v121
	v_mul_f32_e32 v52, v52, v121
	v_mul_f32_e32 v53, v53, v121
	v_mul_f32_e32 v50, v50, v98
	v_mul_f32_e32 v51, v51, v99
	v_mul_f32_e32 v52, v52, v100
	v_mul_f32_e32 v53, v53, v101
	v_cvt_pk_bf16_f32 v50, v50, v51
	v_cvt_pk_bf16_f32 v51, v52, v53
	global_store_dwordx2 v116, v[50:51], s[88:89] offset:0
	v_mul_f32_e32 v54, v54, v121
	v_mul_f32_e32 v55, v55, v121
	v_mul_f32_e32 v56, v56, v121
	v_mul_f32_e32 v57, v57, v121
	v_mul_f32_e32 v54, v54, v102
	v_mul_f32_e32 v55, v55, v103
	v_mul_f32_e32 v56, v56, v104
	v_mul_f32_e32 v57, v57, v105
	v_cvt_pk_bf16_f32 v54, v54, v55
	v_cvt_pk_bf16_f32 v55, v56, v57
	global_store_dwordx2 v116, v[54:55], s[88:89] offset:32
	v_mul_f32_e32 v58, v58, v121
	v_mul_f32_e32 v59, v59, v121
	v_mul_f32_e32 v60, v60, v121
	v_mul_f32_e32 v61, v61, v121
	v_mul_f32_e32 v58, v58, v106
	v_mul_f32_e32 v59, v59, v107
	v_mul_f32_e32 v60, v60, v108
	v_mul_f32_e32 v61, v61, v109
	v_cvt_pk_bf16_f32 v58, v58, v59
	v_cvt_pk_bf16_f32 v59, v60, v61
	global_store_dwordx2 v116, v[58:59], s[88:89] offset:64
	v_mul_f32_e32 v62, v62, v121
	v_mul_f32_e32 v63, v63, v121
	v_mul_f32_e32 v64, v64, v121
	v_mul_f32_e32 v65, v65, v121
	v_mul_f32_e32 v62, v62, v110
	v_mul_f32_e32 v63, v63, v111
	v_mul_f32_e32 v64, v64, v112
	v_mul_f32_e32 v65, v65, v113
	v_cvt_pk_bf16_f32 v62, v62, v63
	v_cvt_pk_bf16_f32 v63, v64, v65
	global_store_dwordx2 v116, v[62:63], s[88:89] offset:96
	s_waitcnt vmcnt(16)
	s_cmp_lg_u32 s81, 0
	s_cbranch_scc1 .Lconv_lo_ok
	v_mov_b32_e32 v130, 0
	v_mov_b32_e32 v131, 0
	v_mov_b32_e32 v132, 0
	v_mov_b32_e32 v133, 0
.Lconv_lo_ok:
	s_add_u32 s51, s81, 8
	s_cmp_lt_u32 s51, s77
	s_cbranch_scc1 .Lconv_hi_ok
	v_mov_b32_e32 v166, 0
	v_mov_b32_e32 v167, 0
	v_mov_b32_e32 v168, 0
	v_mov_b32_e32 v169, 0
.Lconv_hi_ok:
	v_lshlrev_b32_e32 v98, 16, v130
	v_and_b32_e32 v99, 0xffff0000, v130
	v_lshlrev_b32_e32 v100, 16, v131
	v_and_b32_e32 v101, 0xffff0000, v131
	v_lshlrev_b32_e32 v102, 16, v132
	v_and_b32_e32 v103, 0xffff0000, v132
	v_lshlrev_b32_e32 v104, 16, v133
	v_and_b32_e32 v105, 0xffff0000, v133
	v_lshlrev_b32_e32 v106, 16, v134
	v_and_b32_e32 v107, 0xffff0000, v134
	v_lshlrev_b32_e32 v108, 16, v135
	v_and_b32_e32 v109, 0xffff0000, v135
	v_lshlrev_b32_e32 v110, 16, v136
	v_and_b32_e32 v111, 0xffff0000, v136
	v_lshlrev_b32_e32 v112, 16, v137
	v_and_b32_e32 v113, 0xffff0000, v137
	v_lshlrev_b32_e32 v114, 16, v138
	v_and_b32_e32 v115, 0xffff0000, v138
	v_lshlrev_b32_e32 v116, 16, v139
	v_and_b32_e32 v117, 0xffff0000, v139
	v_lshlrev_b32_e32 v118, 16, v140
	v_and_b32_e32 v119, 0xffff0000, v140
	v_lshlrev_b32_e32 v120, 16, v141
	v_and_b32_e32 v121, 0xffff0000, v141
	v_lshlrev_b32_e32 v122, 16, v66
	v_and_b32_e32 v123, 0xffff0000, v66
	v_lshlrev_b32_e32 v124, 16, v67
	v_and_b32_e32 v125, 0xffff0000, v67
	v_lshlrev_b32_e32 v126, 16, v68
	v_and_b32_e32 v127, 0xffff0000, v68
	v_lshlrev_b32_e32 v128, 16, v69
	v_and_b32_e32 v129, 0xffff0000, v69
	v_pk_mul_f32 v[2:3], v[194:195], v[98:99]
	v_pk_mul_f32 v[4:5], v[196:197], v[100:101]
	v_pk_mul_f32 v[6:7], v[198:199], v[102:103]
	v_pk_mul_f32 v[8:9], v[200:201], v[104:105]
	v_pk_fma_f32 v[2:3], v[202:203], v[106:107], v[2:3]
	v_pk_fma_f32 v[4:5], v[204:205], v[108:109], v[4:5]
	v_pk_fma_f32 v[6:7], v[206:207], v[110:111], v[6:7]
	v_pk_fma_f32 v[8:9], v[208:209], v[112:113], v[8:9]
	v_pk_fma_f32 v[2:3], v[210:211], v[114:115], v[2:3]
	v_pk_fma_f32 v[4:5], v[212:213], v[116:117], v[4:5]
	v_pk_fma_f32 v[6:7], v[230:231], v[118:119], v[6:7]
	v_pk_fma_f32 v[8:9], v[232:233], v[120:121], v[8:9]
	v_pk_mul_f32 v[2:3], v[122:123], v[2:3]
	v_pk_mul_f32 v[4:5], v[124:125], v[4:5]
	v_pk_mul_f32 v[6:7], v[126:127], v[6:7]
	v_pk_mul_f32 v[8:9], v[128:129], v[8:9]
	v_mul_f32_e32 v242, v2, v2
	v_fmac_f32_e32 v242, v3, v3
	v_fmac_f32_e32 v242, v4, v4
	v_fmac_f32_e32 v242, v5, v5
	v_fmac_f32_e32 v242, v6, v6
	v_fmac_f32_e32 v242, v7, v7
	v_fmac_f32_e32 v242, v8, v8
	v_fmac_f32_e32 v242, v9, v9
	v_lshlrev_b32_e32 v98, 16, v142
	v_and_b32_e32 v99, 0xffff0000, v142
	v_lshlrev_b32_e32 v100, 16, v143
	v_and_b32_e32 v101, 0xffff0000, v143
	v_lshlrev_b32_e32 v102, 16, v144
	v_and_b32_e32 v103, 0xffff0000, v144
	v_lshlrev_b32_e32 v104, 16, v145
	v_and_b32_e32 v105, 0xffff0000, v145
	v_lshlrev_b32_e32 v122, 16, v70
	v_and_b32_e32 v123, 0xffff0000, v70
	v_lshlrev_b32_e32 v124, 16, v71
	v_and_b32_e32 v125, 0xffff0000, v71
	v_lshlrev_b32_e32 v126, 16, v72
	v_and_b32_e32 v127, 0xffff0000, v72
	v_lshlrev_b32_e32 v128, 16, v73
	v_and_b32_e32 v129, 0xffff0000, v73
	v_pk_mul_f32 v[10:11], v[194:195], v[106:107]
	v_pk_mul_f32 v[12:13], v[196:197], v[108:109]
	v_pk_mul_f32 v[14:15], v[198:199], v[110:111]
	v_pk_mul_f32 v[16:17], v[200:201], v[112:113]
	v_pk_fma_f32 v[10:11], v[202:203], v[114:115], v[10:11]
	v_pk_fma_f32 v[12:13], v[204:205], v[116:117], v[12:13]
	v_pk_fma_f32 v[14:15], v[206:207], v[118:119], v[14:15]
	v_pk_fma_f32 v[16:17], v[208:209], v[120:121], v[16:17]
	v_pk_fma_f32 v[10:11], v[210:211], v[98:99], v[10:11]
	v_pk_fma_f32 v[12:13], v[212:213], v[100:101], v[12:13]
	v_pk_fma_f32 v[14:15], v[230:231], v[102:103], v[14:15]
	v_pk_fma_f32 v[16:17], v[232:233], v[104:105], v[16:17]
	v_pk_mul_f32 v[10:11], v[122:123], v[10:11]
	v_pk_mul_f32 v[12:13], v[124:125], v[12:13]
	v_pk_mul_f32 v[14:15], v[126:127], v[14:15]
	v_pk_mul_f32 v[16:17], v[128:129], v[16:17]
	v_mul_f32_e32 v243, v10, v10
	v_fmac_f32_e32 v243, v11, v11
	v_fmac_f32_e32 v243, v12, v12
	v_fmac_f32_e32 v243, v13, v13
	v_fmac_f32_e32 v243, v14, v14
	v_fmac_f32_e32 v243, v15, v15
	v_fmac_f32_e32 v243, v16, v16
	v_fmac_f32_e32 v243, v17, v17
	v_lshlrev_b32_e32 v106, 16, v146
	v_and_b32_e32 v107, 0xffff0000, v146
	v_lshlrev_b32_e32 v108, 16, v147
	v_and_b32_e32 v109, 0xffff0000, v147
	v_lshlrev_b32_e32 v110, 16, v148
	v_and_b32_e32 v111, 0xffff0000, v148
	v_lshlrev_b32_e32 v112, 16, v149
	v_and_b32_e32 v113, 0xffff0000, v149
	v_lshlrev_b32_e32 v122, 16, v74
	v_and_b32_e32 v123, 0xffff0000, v74
	v_lshlrev_b32_e32 v124, 16, v75
	v_and_b32_e32 v125, 0xffff0000, v75
	v_lshlrev_b32_e32 v126, 16, v76
	v_and_b32_e32 v127, 0xffff0000, v76
	v_lshlrev_b32_e32 v128, 16, v77
	v_and_b32_e32 v129, 0xffff0000, v77
	v_pk_mul_f32 v[18:19], v[194:195], v[114:115]
	v_pk_mul_f32 v[20:21], v[196:197], v[116:117]
	v_pk_mul_f32 v[22:23], v[198:199], v[118:119]
	v_pk_mul_f32 v[24:25], v[200:201], v[120:121]
	v_pk_fma_f32 v[18:19], v[202:203], v[98:99], v[18:19]
	v_pk_fma_f32 v[20:21], v[204:205], v[100:101], v[20:21]
	v_pk_fma_f32 v[22:23], v[206:207], v[102:103], v[22:23]
	v_pk_fma_f32 v[24:25], v[208:209], v[104:105], v[24:25]
	v_pk_fma_f32 v[18:19], v[210:211], v[106:107], v[18:19]
	v_pk_fma_f32 v[20:21], v[212:213], v[108:109], v[20:21]
	v_pk_fma_f32 v[22:23], v[230:231], v[110:111], v[22:23]
	v_pk_fma_f32 v[24:25], v[232:233], v[112:113], v[24:25]
	v_pk_mul_f32 v[18:19], v[122:123], v[18:19]
	v_pk_mul_f32 v[20:21], v[124:125], v[20:21]
	v_pk_mul_f32 v[22:23], v[126:127], v[22:23]
	v_pk_mul_f32 v[24:25], v[128:129], v[24:25]
	v_mul_f32_e32 v244, v18, v18
	v_fmac_f32_e32 v244, v19, v19
	v_fmac_f32_e32 v244, v20, v20
	v_fmac_f32_e32 v244, v21, v21
	v_fmac_f32_e32 v244, v22, v22
	v_fmac_f32_e32 v244, v23, v23
	v_fmac_f32_e32 v244, v24, v24
	v_fmac_f32_e32 v244, v25, v25
	v_lshlrev_b32_e32 v114, 16, v150
	v_and_b32_e32 v115, 0xffff0000, v150
	v_lshlrev_b32_e32 v116, 16, v151
	v_and_b32_e32 v117, 0xffff0000, v151
	v_lshlrev_b32_e32 v118, 16, v152
	v_and_b32_e32 v119, 0xffff0000, v152
	v_lshlrev_b32_e32 v120, 16, v153
	v_and_b32_e32 v121, 0xffff0000, v153
	v_lshlrev_b32_e32 v122, 16, v78
	v_and_b32_e32 v123, 0xffff0000, v78
	v_lshlrev_b32_e32 v124, 16, v79
	v_and_b32_e32 v125, 0xffff0000, v79
	v_lshlrev_b32_e32 v126, 16, v80
	v_and_b32_e32 v127, 0xffff0000, v80
	v_lshlrev_b32_e32 v128, 16, v81
	v_and_b32_e32 v129, 0xffff0000, v81
	v_pk_mul_f32 v[26:27], v[194:195], v[98:99]
	v_pk_mul_f32 v[28:29], v[196:197], v[100:101]
	v_pk_mul_f32 v[30:31], v[198:199], v[102:103]
	v_pk_mul_f32 v[32:33], v[200:201], v[104:105]
	v_pk_fma_f32 v[26:27], v[202:203], v[106:107], v[26:27]
	v_pk_fma_f32 v[28:29], v[204:205], v[108:109], v[28:29]
	v_pk_fma_f32 v[30:31], v[206:207], v[110:111], v[30:31]
	v_pk_fma_f32 v[32:33], v[208:209], v[112:113], v[32:33]
	v_pk_fma_f32 v[26:27], v[210:211], v[114:115], v[26:27]
	v_pk_fma_f32 v[28:29], v[212:213], v[116:117], v[28:29]
	v_pk_fma_f32 v[30:31], v[230:231], v[118:119], v[30:31]
	v_pk_fma_f32 v[32:33], v[232:233], v[120:121], v[32:33]
	v_pk_mul_f32 v[26:27], v[122:123], v[26:27]
	v_pk_mul_f32 v[28:29], v[124:125], v[28:29]
	v_pk_mul_f32 v[30:31], v[126:127], v[30:31]
	v_pk_mul_f32 v[32:33], v[128:129], v[32:33]
	v_mul_f32_e32 v245, v26, v26
	v_fmac_f32_e32 v245, v27, v27
	v_fmac_f32_e32 v245, v28, v28
	v_fmac_f32_e32 v245, v29, v29
	v_fmac_f32_e32 v245, v30, v30
	v_fmac_f32_e32 v245, v31, v31
	v_fmac_f32_e32 v245, v32, v32
	v_fmac_f32_e32 v245, v33, v33
	v_lshlrev_b32_e32 v98, 16, v154
	v_and_b32_e32 v99, 0xffff0000, v154
	v_lshlrev_b32_e32 v100, 16, v155
	v_and_b32_e32 v101, 0xffff0000, v155
	v_lshlrev_b32_e32 v102, 16, v156
	v_and_b32_e32 v103, 0xffff0000, v156
	v_lshlrev_b32_e32 v104, 16, v157
	v_and_b32_e32 v105, 0xffff0000, v157
	v_lshlrev_b32_e32 v122, 16, v82
	v_and_b32_e32 v123, 0xffff0000, v82
	v_lshlrev_b32_e32 v124, 16, v83
	v_and_b32_e32 v125, 0xffff0000, v83
	v_lshlrev_b32_e32 v126, 16, v84
	v_and_b32_e32 v127, 0xffff0000, v84
	v_lshlrev_b32_e32 v128, 16, v85
	v_and_b32_e32 v129, 0xffff0000, v85
	v_pk_mul_f32 v[34:35], v[194:195], v[106:107]
	v_pk_mul_f32 v[36:37], v[196:197], v[108:109]
	v_pk_mul_f32 v[38:39], v[198:199], v[110:111]
	v_pk_mul_f32 v[40:41], v[200:201], v[112:113]
	v_pk_fma_f32 v[34:35], v[202:203], v[114:115], v[34:35]
	v_pk_fma_f32 v[36:37], v[204:205], v[116:117], v[36:37]
	v_pk_fma_f32 v[38:39], v[206:207], v[118:119], v[38:39]
	v_pk_fma_f32 v[40:41], v[208:209], v[120:121], v[40:41]
	v_pk_fma_f32 v[34:35], v[210:211], v[98:99], v[34:35]
	v_pk_fma_f32 v[36:37], v[212:213], v[100:101], v[36:37]
	v_pk_fma_f32 v[38:39], v[230:231], v[102:103], v[38:39]
	v_pk_fma_f32 v[40:41], v[232:233], v[104:105], v[40:41]
	v_pk_mul_f32 v[34:35], v[122:123], v[34:35]
	v_pk_mul_f32 v[36:37], v[124:125], v[36:37]
	v_pk_mul_f32 v[38:39], v[126:127], v[38:39]
	v_pk_mul_f32 v[40:41], v[128:129], v[40:41]
	v_mul_f32_e32 v248, v34, v34
	v_fmac_f32_e32 v248, v35, v35
	v_fmac_f32_e32 v248, v36, v36
	v_fmac_f32_e32 v248, v37, v37
	v_fmac_f32_e32 v248, v38, v38
	v_fmac_f32_e32 v248, v39, v39
	v_fmac_f32_e32 v248, v40, v40
	v_fmac_f32_e32 v248, v41, v41
	v_lshlrev_b32_e32 v106, 16, v158
	v_and_b32_e32 v107, 0xffff0000, v158
	v_lshlrev_b32_e32 v108, 16, v159
	v_and_b32_e32 v109, 0xffff0000, v159
	v_lshlrev_b32_e32 v110, 16, v160
	v_and_b32_e32 v111, 0xffff0000, v160
	v_lshlrev_b32_e32 v112, 16, v161
	v_and_b32_e32 v113, 0xffff0000, v161
	v_lshlrev_b32_e32 v122, 16, v86
	v_and_b32_e32 v123, 0xffff0000, v86
	v_lshlrev_b32_e32 v124, 16, v87
	v_and_b32_e32 v125, 0xffff0000, v87
	v_lshlrev_b32_e32 v126, 16, v88
	v_and_b32_e32 v127, 0xffff0000, v88
	v_lshlrev_b32_e32 v128, 16, v89
	v_and_b32_e32 v129, 0xffff0000, v89
	v_pk_mul_f32 v[42:43], v[194:195], v[114:115]
	v_pk_mul_f32 v[44:45], v[196:197], v[116:117]
	v_pk_mul_f32 v[46:47], v[198:199], v[118:119]
	v_pk_mul_f32 v[48:49], v[200:201], v[120:121]
	v_pk_fma_f32 v[42:43], v[202:203], v[98:99], v[42:43]
	v_pk_fma_f32 v[44:45], v[204:205], v[100:101], v[44:45]
	v_pk_fma_f32 v[46:47], v[206:207], v[102:103], v[46:47]
	v_pk_fma_f32 v[48:49], v[208:209], v[104:105], v[48:49]
	v_pk_fma_f32 v[42:43], v[210:211], v[106:107], v[42:43]
	v_pk_fma_f32 v[44:45], v[212:213], v[108:109], v[44:45]
	v_pk_fma_f32 v[46:47], v[230:231], v[110:111], v[46:47]
	v_pk_fma_f32 v[48:49], v[232:233], v[112:113], v[48:49]
	v_pk_mul_f32 v[42:43], v[122:123], v[42:43]
	v_pk_mul_f32 v[44:45], v[124:125], v[44:45]
	v_pk_mul_f32 v[46:47], v[126:127], v[46:47]
	v_pk_mul_f32 v[48:49], v[128:129], v[48:49]
	v_mul_f32_e32 v249, v42, v42
	v_fmac_f32_e32 v249, v43, v43
	v_fmac_f32_e32 v249, v44, v44
	v_fmac_f32_e32 v249, v45, v45
	v_fmac_f32_e32 v249, v46, v46
	v_fmac_f32_e32 v249, v47, v47
	v_fmac_f32_e32 v249, v48, v48
	v_fmac_f32_e32 v249, v49, v49
	v_lshlrev_b32_e32 v114, 16, v162
	v_and_b32_e32 v115, 0xffff0000, v162
	v_lshlrev_b32_e32 v116, 16, v163
	v_and_b32_e32 v117, 0xffff0000, v163
	v_lshlrev_b32_e32 v118, 16, v164
	v_and_b32_e32 v119, 0xffff0000, v164
	v_lshlrev_b32_e32 v120, 16, v165
	v_and_b32_e32 v121, 0xffff0000, v165
	v_lshlrev_b32_e32 v122, 16, v90
	v_and_b32_e32 v123, 0xffff0000, v90
	v_lshlrev_b32_e32 v124, 16, v91
	v_and_b32_e32 v125, 0xffff0000, v91
	v_lshlrev_b32_e32 v126, 16, v92
	v_and_b32_e32 v127, 0xffff0000, v92
	v_lshlrev_b32_e32 v128, 16, v93
	v_and_b32_e32 v129, 0xffff0000, v93
	v_pk_mul_f32 v[50:51], v[194:195], v[98:99]
	v_pk_mul_f32 v[52:53], v[196:197], v[100:101]
	v_pk_mul_f32 v[54:55], v[198:199], v[102:103]
	v_pk_mul_f32 v[56:57], v[200:201], v[104:105]
	v_pk_fma_f32 v[50:51], v[202:203], v[106:107], v[50:51]
	v_pk_fma_f32 v[52:53], v[204:205], v[108:109], v[52:53]
	v_pk_fma_f32 v[54:55], v[206:207], v[110:111], v[54:55]
	v_pk_fma_f32 v[56:57], v[208:209], v[112:113], v[56:57]
	v_pk_fma_f32 v[50:51], v[210:211], v[114:115], v[50:51]
	v_pk_fma_f32 v[52:53], v[212:213], v[116:117], v[52:53]
	v_pk_fma_f32 v[54:55], v[230:231], v[118:119], v[54:55]
	v_pk_fma_f32 v[56:57], v[232:233], v[120:121], v[56:57]
	v_pk_mul_f32 v[50:51], v[122:123], v[50:51]
	v_pk_mul_f32 v[52:53], v[124:125], v[52:53]
	v_pk_mul_f32 v[54:55], v[126:127], v[54:55]
	v_pk_mul_f32 v[56:57], v[128:129], v[56:57]
	v_mul_f32_e32 v250, v50, v50
	v_fmac_f32_e32 v250, v51, v51
	v_fmac_f32_e32 v250, v52, v52
	v_fmac_f32_e32 v250, v53, v53
	v_fmac_f32_e32 v250, v54, v54
	v_fmac_f32_e32 v250, v55, v55
	v_fmac_f32_e32 v250, v56, v56
	v_fmac_f32_e32 v250, v57, v57
	v_lshlrev_b32_e32 v98, 16, v166
	v_and_b32_e32 v99, 0xffff0000, v166
	v_lshlrev_b32_e32 v100, 16, v167
	v_and_b32_e32 v101, 0xffff0000, v167
	v_lshlrev_b32_e32 v102, 16, v168
	v_and_b32_e32 v103, 0xffff0000, v168
	v_lshlrev_b32_e32 v104, 16, v169
	v_and_b32_e32 v105, 0xffff0000, v169
	v_lshlrev_b32_e32 v122, 16, v94
	v_and_b32_e32 v123, 0xffff0000, v94
	v_lshlrev_b32_e32 v124, 16, v95
	v_and_b32_e32 v125, 0xffff0000, v95
	v_lshlrev_b32_e32 v126, 16, v96
	v_and_b32_e32 v127, 0xffff0000, v96
	v_lshlrev_b32_e32 v128, 16, v97
	v_and_b32_e32 v129, 0xffff0000, v97
	v_pk_mul_f32 v[58:59], v[194:195], v[106:107]
	v_pk_mul_f32 v[60:61], v[196:197], v[108:109]
	v_pk_mul_f32 v[62:63], v[198:199], v[110:111]
	v_pk_mul_f32 v[64:65], v[200:201], v[112:113]
	v_pk_fma_f32 v[58:59], v[202:203], v[114:115], v[58:59]
	v_pk_fma_f32 v[60:61], v[204:205], v[116:117], v[60:61]
	v_pk_fma_f32 v[62:63], v[206:207], v[118:119], v[62:63]
	v_pk_fma_f32 v[64:65], v[208:209], v[120:121], v[64:65]
	v_pk_fma_f32 v[58:59], v[210:211], v[98:99], v[58:59]
	v_pk_fma_f32 v[60:61], v[212:213], v[100:101], v[60:61]
	v_pk_fma_f32 v[62:63], v[230:231], v[102:103], v[62:63]
	v_pk_fma_f32 v[64:65], v[232:233], v[104:105], v[64:65]
	v_pk_mul_f32 v[58:59], v[122:123], v[58:59]
	v_pk_mul_f32 v[60:61], v[124:125], v[60:61]
	v_pk_mul_f32 v[62:63], v[126:127], v[62:63]
	v_pk_mul_f32 v[64:65], v[128:129], v[64:65]
	v_mul_f32_e32 v251, v58, v58
	v_fmac_f32_e32 v251, v59, v59
	v_fmac_f32_e32 v251, v60, v60
	v_fmac_f32_e32 v251, v61, v61
	v_fmac_f32_e32 v251, v62, v62
	v_fmac_f32_e32 v251, v63, v63
	v_fmac_f32_e32 v251, v64, v64
	v_fmac_f32_e32 v251, v65, v65
	ds_bpermute_b32 v225, v216, v242
	ds_bpermute_b32 v226, v216, v243
	ds_bpermute_b32 v227, v216, v244
	ds_bpermute_b32 v229, v216, v245
	ds_bpermute_b32 v214, v216, v248
	ds_bpermute_b32 v215, v216, v249
	ds_bpermute_b32 v0, v216, v250
	ds_bpermute_b32 v247, v216, v251
	s_waitcnt lgkmcnt(0)
	v_add_f32_e32 v242, v242, v225
	v_add_f32_e32 v243, v243, v226
	v_add_f32_e32 v244, v244, v227
	v_add_f32_e32 v245, v245, v229
	v_add_f32_e32 v248, v248, v214
	v_add_f32_e32 v249, v249, v215
	v_add_f32_e32 v250, v250, v0
	v_add_f32_e32 v251, v251, v247
	ds_bpermute_b32 v225, v217, v242
	ds_bpermute_b32 v226, v217, v243
	ds_bpermute_b32 v227, v217, v244
	ds_bpermute_b32 v229, v217, v245
	ds_bpermute_b32 v214, v217, v248
	ds_bpermute_b32 v215, v217, v249
	ds_bpermute_b32 v0, v217, v250
	ds_bpermute_b32 v247, v217, v251
	s_waitcnt lgkmcnt(0)
	v_add_f32_e32 v242, v242, v225
	v_add_f32_e32 v243, v243, v226
	v_add_f32_e32 v244, v244, v227
	v_add_f32_e32 v245, v245, v229
	v_add_f32_e32 v248, v248, v214
	v_add_f32_e32 v249, v249, v215
	v_add_f32_e32 v250, v250, v0
	v_add_f32_e32 v251, v251, v247
	ds_bpermute_b32 v225, v218, v242
	ds_bpermute_b32 v226, v218, v243
	ds_bpermute_b32 v227, v218, v244
	ds_bpermute_b32 v229, v218, v245
	ds_bpermute_b32 v214, v218, v248
	ds_bpermute_b32 v215, v218, v249
	ds_bpermute_b32 v0, v218, v250
	ds_bpermute_b32 v247, v218, v251
	s_waitcnt lgkmcnt(0)
	v_add_f32_e32 v242, v242, v225
	v_add_f32_e32 v243, v243, v226
	v_add_f32_e32 v244, v244, v227
	v_add_f32_e32 v245, v245, v229
	v_add_f32_e32 v248, v248, v214
	v_add_f32_e32 v249, v249, v215
	v_add_f32_e32 v250, v250, v0
	v_add_f32_e32 v251, v251, v247
	v_fmamk_f32 v242, v242, 0x3c800000, v224
	v_fmamk_f32 v243, v243, 0x3c800000, v224
	v_fmamk_f32 v244, v244, 0x3c800000, v224
	v_fmamk_f32 v245, v245, 0x3c800000, v224
	v_fmamk_f32 v248, v248, 0x3c800000, v224
	v_fmamk_f32 v249, v249, 0x3c800000, v224
	v_fmamk_f32 v250, v250, 0x3c800000, v224
	v_fmamk_f32 v251, v251, 0x3c800000, v224
	v_rsq_f32_e32 v242, v242
	v_rsq_f32_e32 v243, v243
	v_rsq_f32_e32 v244, v244
	v_rsq_f32_e32 v245, v245
	v_rsq_f32_e32 v248, v248
	v_rsq_f32_e32 v249, v249
	v_rsq_f32_e32 v250, v250
	v_rsq_f32_e32 v251, v251
	s_add_u32 s51, s81, s46
	s_lshl_b32 s51, s51, 11
	s_add_u32 s90, s30, 0x2c000000
	s_addc_u32 s91, s31, 0
	s_add_u32 s90, s90, s51
	s_addc_u32 s91, s91, 0
	v_mul_f32_e32 v2, v2, v242
	v_mul_f32_e32 v3, v3, v242
	v_mul_f32_e32 v4, v4, v242
	v_mul_f32_e32 v5, v5, v242
	v_mul_f32_e32 v6, v6, v242
	v_mul_f32_e32 v7, v7, v242
	v_mul_f32_e32 v8, v8, v242
	v_mul_f32_e32 v9, v9, v242
	v_pk_mul_f32 v[2:3], v[2:3], v[234:235]
	v_pk_mul_f32 v[4:5], v[4:5], v[236:237]
	v_pk_mul_f32 v[6:7], v[6:7], v[238:239]
	v_pk_mul_f32 v[8:9], v[8:9], v[240:241]
	v_cvt_pk_bf16_f32 v2, v2, v3
	v_cvt_pk_bf16_f32 v3, v4, v5
	v_cvt_pk_bf16_f32 v4, v6, v7
	v_cvt_pk_bf16_f32 v5, v8, v9
	global_store_dwordx4 v246, v[2:5], s[90:91] offset:1024
	v_mul_f32_e32 v10, v10, v243
	v_mul_f32_e32 v11, v11, v243
	v_mul_f32_e32 v12, v12, v243
	v_mul_f32_e32 v13, v13, v243
	v_mul_f32_e32 v14, v14, v243
	v_mul_f32_e32 v15, v15, v243
	v_mul_f32_e32 v16, v16, v243
	v_mul_f32_e32 v17, v17, v243
	v_pk_mul_f32 v[10:11], v[10:11], v[234:235]
	v_pk_mul_f32 v[12:13], v[12:13], v[236:237]
	v_pk_mul_f32 v[14:15], v[14:15], v[238:239]
	v_pk_mul_f32 v[16:17], v[16:17], v[240:241]
	v_cvt_pk_bf16_f32 v10, v10, v11
	v_cvt_pk_bf16_f32 v11, v12, v13
	v_cvt_pk_bf16_f32 v12, v14, v15
	v_cvt_pk_bf16_f32 v13, v16, v17
	global_store_dwordx4 v246, v[10:13], s[90:91] offset:3072
	s_add_u32 s90, s90, 0x1000
	s_addc_u32 s91, s91, 0
	v_mul_f32_e32 v18, v18, v244
	v_mul_f32_e32 v19, v19, v244
	v_mul_f32_e32 v20, v20, v244
	v_mul_f32_e32 v21, v21, v244
	v_mul_f32_e32 v22, v22, v244
	v_mul_f32_e32 v23, v23, v244
	v_mul_f32_e32 v24, v24, v244
	v_mul_f32_e32 v25, v25, v244
	v_pk_mul_f32 v[18:19], v[18:19], v[234:235]
	v_pk_mul_f32 v[20:21], v[20:21], v[236:237]
	v_pk_mul_f32 v[22:23], v[22:23], v[238:239]
	v_pk_mul_f32 v[24:25], v[24:25], v[240:241]
	v_cvt_pk_bf16_f32 v18, v18, v19
	v_cvt_pk_bf16_f32 v19, v20, v21
	v_cvt_pk_bf16_f32 v20, v22, v23
	v_cvt_pk_bf16_f32 v21, v24, v25
	global_store_dwordx4 v246, v[18:21], s[90:91] offset:1024
	v_mul_f32_e32 v26, v26, v245
	v_mul_f32_e32 v27, v27, v245
	v_mul_f32_e32 v28, v28, v245
	v_mul_f32_e32 v29, v29, v245
	v_mul_f32_e32 v30, v30, v245
	v_mul_f32_e32 v31, v31, v245
	v_mul_f32_e32 v32, v32, v245
	v_mul_f32_e32 v33, v33, v245
	v_pk_mul_f32 v[26:27], v[26:27], v[234:235]
	v_pk_mul_f32 v[28:29], v[28:29], v[236:237]
	v_pk_mul_f32 v[30:31], v[30:31], v[238:239]
	v_pk_mul_f32 v[32:33], v[32:33], v[240:241]
	v_cvt_pk_bf16_f32 v26, v26, v27
	v_cvt_pk_bf16_f32 v27, v28, v29
	v_cvt_pk_bf16_f32 v28, v30, v31
	v_cvt_pk_bf16_f32 v29, v32, v33
	global_store_dwordx4 v246, v[26:29], s[90:91] offset:3072
	s_add_u32 s90, s90, 0x1000
	s_addc_u32 s91, s91, 0
	v_mul_f32_e32 v34, v34, v248
	v_mul_f32_e32 v35, v35, v248
	v_mul_f32_e32 v36, v36, v248
	v_mul_f32_e32 v37, v37, v248
	v_mul_f32_e32 v38, v38, v248
	v_mul_f32_e32 v39, v39, v248
	v_mul_f32_e32 v40, v40, v248
	v_mul_f32_e32 v41, v41, v248
	v_pk_mul_f32 v[34:35], v[34:35], v[234:235]
	v_pk_mul_f32 v[36:37], v[36:37], v[236:237]
	v_pk_mul_f32 v[38:39], v[38:39], v[238:239]
	v_pk_mul_f32 v[40:41], v[40:41], v[240:241]
	v_cvt_pk_bf16_f32 v34, v34, v35
	v_cvt_pk_bf16_f32 v35, v36, v37
	v_cvt_pk_bf16_f32 v36, v38, v39
	v_cvt_pk_bf16_f32 v37, v40, v41
	global_store_dwordx4 v246, v[34:37], s[90:91] offset:1024
	v_mul_f32_e32 v42, v42, v249
	v_mul_f32_e32 v43, v43, v249
	v_mul_f32_e32 v44, v44, v249
	v_mul_f32_e32 v45, v45, v249
	v_mul_f32_e32 v46, v46, v249
	v_mul_f32_e32 v47, v47, v249
	v_mul_f32_e32 v48, v48, v249
	v_mul_f32_e32 v49, v49, v249
	v_pk_mul_f32 v[42:43], v[42:43], v[234:235]
	v_pk_mul_f32 v[44:45], v[44:45], v[236:237]
	v_pk_mul_f32 v[46:47], v[46:47], v[238:239]
	v_pk_mul_f32 v[48:49], v[48:49], v[240:241]
	v_cvt_pk_bf16_f32 v42, v42, v43
	v_cvt_pk_bf16_f32 v43, v44, v45
	v_cvt_pk_bf16_f32 v44, v46, v47
	v_cvt_pk_bf16_f32 v45, v48, v49
	global_store_dwordx4 v246, v[42:45], s[90:91] offset:3072
	s_add_u32 s90, s90, 0x1000
	s_addc_u32 s91, s91, 0
	v_mul_f32_e32 v50, v50, v250
	v_mul_f32_e32 v51, v51, v250
	v_mul_f32_e32 v52, v52, v250
	v_mul_f32_e32 v53, v53, v250
	v_mul_f32_e32 v54, v54, v250
	v_mul_f32_e32 v55, v55, v250
	v_mul_f32_e32 v56, v56, v250
	v_mul_f32_e32 v57, v57, v250
	v_pk_mul_f32 v[50:51], v[50:51], v[234:235]
	v_pk_mul_f32 v[52:53], v[52:53], v[236:237]
	v_pk_mul_f32 v[54:55], v[54:55], v[238:239]
	v_pk_mul_f32 v[56:57], v[56:57], v[240:241]
	v_cvt_pk_bf16_f32 v50, v50, v51
	v_cvt_pk_bf16_f32 v51, v52, v53
	v_cvt_pk_bf16_f32 v52, v54, v55
	v_cvt_pk_bf16_f32 v53, v56, v57
	global_store_dwordx4 v246, v[50:53], s[90:91] offset:1024
	v_mul_f32_e32 v58, v58, v251
	v_mul_f32_e32 v59, v59, v251
	v_mul_f32_e32 v60, v60, v251
	v_mul_f32_e32 v61, v61, v251
	v_mul_f32_e32 v62, v62, v251
	v_mul_f32_e32 v63, v63, v251
	v_mul_f32_e32 v64, v64, v251
	v_mul_f32_e32 v65, v65, v251
	v_pk_mul_f32 v[58:59], v[58:59], v[234:235]
	v_pk_mul_f32 v[60:61], v[60:61], v[236:237]
	v_pk_mul_f32 v[62:63], v[62:63], v[238:239]
	v_pk_mul_f32 v[64:65], v[64:65], v[240:241]
	v_cvt_pk_bf16_f32 v58, v58, v59
	v_cvt_pk_bf16_f32 v59, v60, v61
	v_cvt_pk_bf16_f32 v60, v62, v63
	v_cvt_pk_bf16_f32 v61, v64, v65
	global_store_dwordx4 v246, v[58:61], s[90:91] offset:3072
	s_branch .LBB0_417

	.amdhsa_kernel _Z7enc_fwd4Args
		.amdhsa_group_segment_fixed_size 0
		.amdhsa_private_segment_fixed_size 0
		.amdhsa_kernarg_size 440
		.amdhsa_user_sgpr_count 2
		.amdhsa_user_sgpr_dispatch_ptr 0
		.amdhsa_user_sgpr_queue_ptr 0
		.amdhsa_user_sgpr_kernarg_segment_ptr 1
		.amdhsa_user_sgpr_dispatch_id 0
		.amdhsa_user_sgpr_kernarg_preload_length 0
		.amdhsa_user_sgpr_kernarg_preload_offset 0
		.amdhsa_user_sgpr_private_segment_size 0
		.amdhsa_uses_dynamic_stack 0
		.amdhsa_enable_private_segment 0
		.amdhsa_system_sgpr_workgroup_id_x 1
		.amdhsa_system_sgpr_workgroup_id_y 0
		.amdhsa_system_sgpr_workgroup_id_z 0
		.amdhsa_system_sgpr_workgroup_info 0
		.amdhsa_system_vgpr_workitem_id 2
		.amdhsa_next_free_vgpr 255
		.amdhsa_next_free_sgpr 102
		.amdhsa_accum_offset 256
		.amdhsa_reserve_vcc 1
		.amdhsa_float_round_mode_32 0
		.amdhsa_float_round_mode_16_64 0
		.amdhsa_float_denorm_mode_32 3
		.amdhsa_float_denorm_mode_16_64 3
		.amdhsa_dx10_clamp 1
		.amdhsa_ieee_mode 1
		.amdhsa_fp16_overflow 0
		.amdhsa_tg_split 0
		.amdhsa_exception_fp_ieee_invalid_op 0
		.amdhsa_exception_fp_denorm_src 0
		.amdhsa_exception_fp_ieee_div_zero 0
		.amdhsa_exception_fp_ieee_overflow 0
		.amdhsa_exception_fp_ieee_underflow 0
		.amdhsa_exception_fp_ieee_inexact 0
		.amdhsa_exception_int_div_zero 0
	.end_amdhsa_kernel

amdhsa.kernels:
  - .agpr_count:     0
    .args:
      - .offset:         0
        .size:           184
        .value_kind:     by_value
      - .offset:         184
        .size:           4
        .value_kind:     hidden_block_count_x
      - .offset:         188
        .size:           4
        .value_kind:     hidden_block_count_y
      - .offset:         192
        .size:           4
        .value_kind:     hidden_block_count_z
      - .offset:         196
        .size:           2
        .value_kind:     hidden_group_size_x
      - .offset:         198
        .size:           2
        .value_kind:     hidden_group_size_y
      - .offset:         200
        .size:           2
        .value_kind:     hidden_group_size_z
      - .offset:         202
        .size:           2
        .value_kind:     hidden_remainder_x
      - .offset:         204
        .size:           2
        .value_kind:     hidden_remainder_y
      - .offset:         206
        .size:           2
        .value_kind:     hidden_remainder_z
      - .offset:         224
        .size:           8
        .value_kind:     hidden_global_offset_x
      - .offset:         232
        .size:           8
        .value_kind:     hidden_global_offset_y
      - .offset:         240
        .size:           8
        .value_kind:     hidden_global_offset_z
      - .offset:         248
        .size:           2
        .value_kind:     hidden_grid_dims
      - .offset:         272
        .size:           8
        .value_kind:     hidden_multigrid_sync_arg
      - .offset:         304
        .size:           4
        .value_kind:     hidden_dynamic_lds_size
    .group_segment_fixed_size: 0
    .kernarg_segment_align: 8
    .kernarg_segment_size: 440
    .language:       OpenCL C
    .language_version:
      - 2
      - 0
    .max_flat_workgroup_size: 512
    .name:           _Z7enc_fwd4Args
    .private_segment_fixed_size: 0
    .sgpr_count:     108
    .sgpr_spill_count: 16
    .symbol:         _Z7enc_fwd4Args.kd
    .uniform_work_group_size: 1
    .uses_dynamic_stack: false
    .vgpr_count:     255
    .vgpr_spill_count: 0
    .wavefront_size: 64
